# GDN: LDS operand reads two tokens ahead (third operand register set) instead of one token + staged waits
# baseline (speedup 1.0000x reference)
.Lgd2_item:
	s_lshr_b32 s2, s27, 4
	s_and_b32 s3, s27, 15
	s_lshl_b32 s4, s3, 4
	v_lshl_add_u32 v154, v5, 2, s4
	v_lshl_add_u32 v153, v154, 1, v4
	s_and_b32 s4, s3, 3
	s_lshl_b32 s4, s4, 5
	v_lshl_add_u32 v3, v5, 3, s4
	s_and_b32 s4, s3, 12
	s_lshl_b32 s4, s4, 4
	v_min_u32_e32 v155, 15, v198
	v_lshl_add_u32 v104, v155, 2, s4
	s_and_b32 s5, s2, 7
	s_lshl_b32 s3, s5, 7
	s_add_u32 s4, s4, s3
	s_add_u32 s4, s4, 2048
	v_lshl_add_u32 v105, v155, 2, s4
	s_lshr_b32 s4, s2, 3
	v_readlane_b32 s3, v255, 15
	s_mul_i32 s6, s4, 0xc00000
	s_mul_i32 s7, s3, 0x1800
	s_add_u32 s6, s6, s7
	s_lshl_b32 s7, s5, 8
	s_add_u32 s6, s6, s7
	s_add_u32 s6, s6, 0xb38d900
	s_add_u32 s8, s24, s6
	s_addc_u32 s9, s25, 0
	s_lshl_b32 s6, s4, 25
	s_lshl_b32 s7, s3, 14
	s_add_u32 s6, s6, s7
	s_lshl_b32 s7, s5, 7
	s_add_u32 s6, s6, s7
	s_add_u32 s6, s6, 62659584
	s_add_u32 s10, s22, s6
	s_addc_u32 s11, s23, 0
	s_lshl_b32 s6, s4, 18
	s_lshl_b32 s7, s3, 7
	s_add_u32 s6, s6, s7
	s_lshl_b32 s7, s5, 4
	s_add_u32 s6, s6, s7
	s_add_u32 s6, s6, 0x37b8400
	s_add_u32 s12, s22, s6
	s_addc_u32 s13, s23, 0
	s_lshl_b32 s6, s4, 23
	s_lshl_b32 s7, s5, 8
	s_add_u32 s6, s6, s7
	s_add_u32 s6, s6, 333186048
	s_add_u32 s14, s22, s6
	s_addc_u32 s15, s23, 0
	s_movk_i32 s18, 256
	s_movk_i32 s19, 16640
	s_mov_b32 s20, 33024
	v_add_u32_e32 v28, s18, v32
	v_add_u32_e32 v29, s18, v33
	v_add_u32_e32 v30, s18, v34
	v_add_u32_e32 v31, s18, v35
	global_load_dword v108, v36, s[8:9]
	global_load_dword v109, v36, s[8:9] offset:-2048
	global_load_dword v111, v104, s[8:9] offset:2048
	global_load_dword v110, v37, s[10:11]
	global_load_dword v112, v105, s[10:11]
	global_load_dword v113, v106, s[12:13]
	s_add_u32 s8, s8, 0xc000
	s_addc_u32 s9, s9, 0
	s_add_u32 s10, s10, 0x20000
	s_addc_u32 s11, s11, 0
	s_add_u32 s12, s12, 0x400
	s_addc_u32 s13, s13, 0
	s_waitcnt vmcnt(0)
	v_lshlrev_b32_e32 v116, 16, v108
	v_lshlrev_b32_e32 v117, 16, v109
	v_and_b32_e32 v118, s17, v108
	v_and_b32_e32 v119, s17, v109
	v_lshlrev_b32_e32 v120, 16, v110
	v_and_b32_e32 v121, s17, v110
	v_lshlrev_b32_e32 v122, 16, v111
	v_and_b32_e32 v123, s17, v111
	v_lshlrev_b32_e32 v124, 16, v112
	v_and_b32_e32 v125, s17, v112
	ds_write_b128 v32, v[116:119] offset:256
	ds_write_b64 v33, v[120:121] offset:256
	ds_write_b64 v34, v[122:123] offset:256
	ds_write_b64 v34, v[124:125] offset:384
	ds_write_b32 v35, v113 offset:256
	v_add_u32_e32 v28, s19, v32
	v_add_u32_e32 v29, s19, v33
	v_add_u32_e32 v30, s19, v34
	v_add_u32_e32 v31, s19, v35
	global_load_dword v108, v36, s[8:9]
	global_load_dword v109, v36, s[8:9] offset:-2048
	global_load_dword v111, v104, s[8:9] offset:2048
	global_load_dword v110, v37, s[10:11]
	global_load_dword v112, v105, s[10:11]
	global_load_dword v113, v106, s[12:13]
	s_add_u32 s8, s8, 0xc000
	s_addc_u32 s9, s9, 0
	s_add_u32 s10, s10, 0x20000
	s_addc_u32 s11, s11, 0
	s_add_u32 s12, s12, 0x400
	s_addc_u32 s13, s13, 0
	s_waitcnt vmcnt(0)
	v_lshlrev_b32_e32 v116, 16, v108
	v_lshlrev_b32_e32 v117, 16, v109
	v_and_b32_e32 v118, s17, v108
	v_and_b32_e32 v119, s17, v109
	v_lshlrev_b32_e32 v120, 16, v110
	v_and_b32_e32 v121, s17, v110
	v_lshlrev_b32_e32 v122, 16, v111
	v_and_b32_e32 v123, s17, v111
	v_lshlrev_b32_e32 v124, 16, v112
	v_and_b32_e32 v125, s17, v112
	ds_write_b128 v32, v[116:119] offset:16640
	ds_write_b64 v33, v[120:121] offset:16640
	ds_write_b64 v34, v[122:123] offset:16640
	ds_write_b64 v34, v[124:125] offset:16768
	ds_write_b32 v35, v113 offset:16640
	v_add_u32_e32 v28, s20, v32
	v_add_u32_e32 v29, s20, v33
	v_add_u32_e32 v30, s20, v34
	v_add_u32_e32 v31, s20, v35
	v_add_u32_e32 v22, s18, v2
	v_add_u32_e32 v23, s18, v3
	v_mov_b32_e32 v24, s18
	v_add_u32_e32 v25, s19, v2
	v_add_u32_e32 v26, s19, v3
	v_mov_b32_e32 v27, s19
	v_mov_b32_e32 v6, 0
	v_mov_b32_e32 v7, 0
	v_mov_b32_e32 v8, 0
	v_mov_b32_e32 v9, 0
	v_mov_b32_e32 v10, 0
	v_mov_b32_e32 v11, 0
	v_mov_b32_e32 v12, 0
	v_mov_b32_e32 v13, 0
	v_mov_b32_e32 v14, 0
	v_mov_b32_e32 v15, 0
	v_mov_b32_e32 v16, 0
	v_mov_b32_e32 v17, 0
	v_mov_b32_e32 v18, 0
	v_mov_b32_e32 v19, 0
	v_mov_b32_e32 v20, 0
	v_mov_b32_e32 v21, 0
	v_mov_b32_e32 v51, 1.0
	s_mov_b32 s16, 0
	s_waitcnt vmcnt(0) lgkmcnt(0)
	s_barrier
	s_setprio 1
	ds_read_b128 v[56:59], v2 offset:256
	ds_read_b128 v[60:63], v2 offset:512
	ds_read_b128 v[64:67], v2 offset:768
	ds_read_b128 v[68:71], v2 offset:1024
	ds_read_b64 v[72:73], v3 offset:12544
	ds_read_b128 v[76:79], v1 offset:14592
	ds_read_b128 v[80:83], v2 offset:1280
	ds_read_b128 v[84:87], v2 offset:1536
	ds_read_b128 v[88:91], v2 offset:1792
	ds_read_b128 v[92:95], v2 offset:2048
	ds_read_b64 v[96:97], v3 offset:12800
	ds_read_b128 v[100:103], v1 offset:14608
.Lgd2_loop:
	global_load_dword v108, v36, s[8:9]
	global_load_dword v109, v36, s[8:9] offset:-2048
	global_load_dword v111, v104, s[8:9] offset:2048
	global_load_dword v110, v37, s[10:11]
	global_load_dword v112, v105, s[10:11]
	global_load_dword v113, v106, s[12:13]
	s_add_u32 s8, s8, 0xc000
	s_addc_u32 s9, s9, 0
	s_add_u32 s10, s10, 0x20000
	s_addc_u32 s11, s11, 0
	s_add_u32 s12, s12, 0x400
	s_addc_u32 s13, s13, 0
	s_waitcnt lgkmcnt(6)
	v_pk_mul_f32 v[38:39], v[6:7], v[56:57] op_sel_hi:[1,0]
	v_pk_mul_f32 v[40:41], v[6:7], v[56:57] op_sel:[0,1] op_sel_hi:[1,1]
	v_pk_fma_f32 v[38:39], v[8:9], v[58:59], v[38:39] op_sel_hi:[1,0,1]
	v_pk_fma_f32 v[40:41], v[8:9], v[58:59], v[40:41] op_sel:[0,1,0] op_sel_hi:[1,1,1]
	v_pk_fma_f32 v[38:39], v[10:11], v[60:61], v[38:39] op_sel_hi:[1,0,1]
	v_pk_fma_f32 v[40:41], v[10:11], v[60:61], v[40:41] op_sel:[0,1,0] op_sel_hi:[1,1,1]
	v_pk_fma_f32 v[38:39], v[12:13], v[62:63], v[38:39] op_sel_hi:[1,0,1]
	v_pk_fma_f32 v[40:41], v[12:13], v[62:63], v[40:41] op_sel:[0,1,0] op_sel_hi:[1,1,1]
	v_pk_fma_f32 v[38:39], v[14:15], v[64:65], v[38:39] op_sel_hi:[1,0,1]
	v_pk_fma_f32 v[40:41], v[14:15], v[64:65], v[40:41] op_sel:[0,1,0] op_sel_hi:[1,1,1]
	v_pk_fma_f32 v[38:39], v[16:17], v[66:67], v[38:39] op_sel_hi:[1,0,1]
	v_pk_fma_f32 v[40:41], v[16:17], v[66:67], v[40:41] op_sel:[0,1,0] op_sel_hi:[1,1,1]
	v_pk_fma_f32 v[38:39], v[18:19], v[68:69], v[38:39] op_sel_hi:[1,0,1]
	v_pk_fma_f32 v[40:41], v[18:19], v[68:69], v[40:41] op_sel:[0,1,0] op_sel_hi:[1,1,1]
	v_pk_fma_f32 v[38:39], v[20:21], v[70:71], v[38:39] op_sel_hi:[1,0,1]
	v_pk_fma_f32 v[40:41], v[20:21], v[70:71], v[40:41] op_sel:[0,1,0] op_sel_hi:[1,1,1]
	v_mul_f32_e32 v50, v76, v51
	v_add_f32_dpp v38, v38, v38 row_ror:8 row_mask:0xf bank_mask:0x3 bound_ctrl:1
	v_add_f32_dpp v39, v39, v39 row_ror:8 row_mask:0xf bank_mask:0x3 bound_ctrl:1
	v_add_f32_dpp v38, v40, v40 row_ror:8 row_mask:0xf bank_mask:0xc bound_ctrl:1
	v_add_f32_dpp v39, v41, v41 row_ror:8 row_mask:0xf bank_mask:0xc bound_ctrl:1
	ds_read_b128 v[126:129], v2 offset:2304
	v_add_f32_dpp v38, v38, v38 row_half_mirror row_mask:0xf bank_mask:0x5 bound_ctrl:1
	v_add_f32_dpp v38, v39, v39 row_half_mirror row_mask:0xf bank_mask:0xa bound_ctrl:1
	ds_read_b128 v[130:133], v2 offset:2560
	ds_read_b128 v[134:137], v2 offset:2816
	v_add_f32_dpp v38, v38, v38 quad_perm:[1,0,3,2] row_mask:0xf bank_mask:0xf bound_ctrl:1
	ds_read_b128 v[138:141], v2 offset:3072
	ds_read_b64 v[142:143], v3 offset:13056
	v_add_f32_dpp v38, v38, v38 quad_perm:[2,3,0,1] row_mask:0xf bank_mask:0xf bound_ctrl:1
	ds_read_b128 v[144:147], v1 offset:14624
	v_cmp_gt_f32_e32 vcc, 0x2b8cbccc, v50
	v_fmac_f32_dpp v72, -v38, v50 row_newbcast:0 row_mask:0xf bank_mask:0xf bound_ctrl:1
	v_fmac_f32_dpp v73, -v38, v50 row_newbcast:4 row_mask:0xf bank_mask:0xf bound_ctrl:1
	v_pk_mul_f32 v[44:45], v[72:73], v[76:77] op_sel:[0,1] op_sel_hi:[1,1]
	v_pk_mul_f32 v[48:49], v[44:45], v[78:79] op_sel_hi:[1,0]
	v_rcp_f32_e32 v52, v50
	s_add_u32 s14, s14, 0x1000
	s_addc_u32 s15, s15, 0
	v_fmac_f32_dpp v48, v38, v50 row_newbcast:8 row_mask:0xf bank_mask:0xf bound_ctrl:1
	v_fmac_f32_dpp v49, v38, v50 row_newbcast:12 row_mask:0xf bank_mask:0xf bound_ctrl:1
	s_cbranch_vccnz .Lgd2_rare0_0
.Lgd2_back0_0:
	v_cvt_pk_bf16_f32 v54, v48, v49
	v_pk_mul_f32 v[46:47], v[44:45], v[52:53] op_sel_hi:[1,0]
	v_pk_fma_f32 v[6:7], v[56:57], v[46:47], v[6:7] op_sel_hi:[0,1,1]
	v_pk_fma_f32 v[8:9], v[58:59], v[46:47], v[8:9] op_sel_hi:[0,1,1]
	v_pk_fma_f32 v[10:11], v[60:61], v[46:47], v[10:11] op_sel_hi:[0,1,1]
	v_pk_fma_f32 v[12:13], v[62:63], v[46:47], v[12:13] op_sel_hi:[0,1,1]
	v_pk_fma_f32 v[14:15], v[64:65], v[46:47], v[14:15] op_sel_hi:[0,1,1]
	v_pk_fma_f32 v[16:17], v[66:67], v[46:47], v[16:17] op_sel_hi:[0,1,1]
	v_pk_fma_f32 v[18:19], v[68:69], v[46:47], v[18:19] op_sel_hi:[0,1,1]
	v_pk_fma_f32 v[20:21], v[70:71], v[46:47], v[20:21] op_sel_hi:[0,1,1]
	global_store_dword v154, v54, s[14:15] offset:-4096
	s_waitcnt lgkmcnt(6)
	v_pk_mul_f32 v[38:39], v[6:7], v[80:81] op_sel_hi:[1,0]
	v_pk_mul_f32 v[40:41], v[6:7], v[80:81] op_sel:[0,1] op_sel_hi:[1,1]
	v_pk_fma_f32 v[38:39], v[8:9], v[82:83], v[38:39] op_sel_hi:[1,0,1]
	v_pk_fma_f32 v[40:41], v[8:9], v[82:83], v[40:41] op_sel:[0,1,0] op_sel_hi:[1,1,1]
	v_pk_fma_f32 v[38:39], v[10:11], v[84:85], v[38:39] op_sel_hi:[1,0,1]
	v_pk_fma_f32 v[40:41], v[10:11], v[84:85], v[40:41] op_sel:[0,1,0] op_sel_hi:[1,1,1]
	v_pk_fma_f32 v[38:39], v[12:13], v[86:87], v[38:39] op_sel_hi:[1,0,1]
	v_pk_fma_f32 v[40:41], v[12:13], v[86:87], v[40:41] op_sel:[0,1,0] op_sel_hi:[1,1,1]
	v_pk_fma_f32 v[38:39], v[14:15], v[88:89], v[38:39] op_sel_hi:[1,0,1]
	v_pk_fma_f32 v[40:41], v[14:15], v[88:89], v[40:41] op_sel:[0,1,0] op_sel_hi:[1,1,1]
	v_pk_fma_f32 v[38:39], v[16:17], v[90:91], v[38:39] op_sel_hi:[1,0,1]
	v_pk_fma_f32 v[40:41], v[16:17], v[90:91], v[40:41] op_sel:[0,1,0] op_sel_hi:[1,1,1]
	v_pk_fma_f32 v[38:39], v[18:19], v[92:93], v[38:39] op_sel_hi:[1,0,1]
	v_pk_fma_f32 v[40:41], v[18:19], v[92:93], v[40:41] op_sel:[0,1,0] op_sel_hi:[1,1,1]
	v_pk_fma_f32 v[38:39], v[20:21], v[94:95], v[38:39] op_sel_hi:[1,0,1]
	v_pk_fma_f32 v[40:41], v[20:21], v[94:95], v[40:41] op_sel:[0,1,0] op_sel_hi:[1,1,1]
	v_mul_f32_e32 v51, v100, v50
	v_add_f32_dpp v38, v38, v38 row_ror:8 row_mask:0xf bank_mask:0x3 bound_ctrl:1
	v_add_f32_dpp v39, v39, v39 row_ror:8 row_mask:0xf bank_mask:0x3 bound_ctrl:1
	v_add_f32_dpp v38, v40, v40 row_ror:8 row_mask:0xf bank_mask:0xc bound_ctrl:1
	v_add_f32_dpp v39, v41, v41 row_ror:8 row_mask:0xf bank_mask:0xc bound_ctrl:1
	ds_read_b128 v[56:59], v2 offset:3328
	v_add_f32_dpp v38, v38, v38 row_half_mirror row_mask:0xf bank_mask:0x5 bound_ctrl:1
	v_add_f32_dpp v38, v39, v39 row_half_mirror row_mask:0xf bank_mask:0xa bound_ctrl:1
	ds_read_b128 v[60:63], v2 offset:3584
	ds_read_b128 v[64:67], v2 offset:3840
	v_add_f32_dpp v38, v38, v38 quad_perm:[1,0,3,2] row_mask:0xf bank_mask:0xf bound_ctrl:1
	ds_read_b128 v[68:71], v2 offset:4096
	ds_read_b64 v[72:73], v3 offset:13312
	v_add_f32_dpp v38, v38, v38 quad_perm:[2,3,0,1] row_mask:0xf bank_mask:0xf bound_ctrl:1
	ds_read_b128 v[76:79], v1 offset:14640
	v_cmp_gt_f32_e32 vcc, 0x2b8cbccc, v51
	v_fmac_f32_dpp v96, -v38, v51 row_newbcast:0 row_mask:0xf bank_mask:0xf bound_ctrl:1
	v_fmac_f32_dpp v97, -v38, v51 row_newbcast:4 row_mask:0xf bank_mask:0xf bound_ctrl:1
	v_pk_mul_f32 v[44:45], v[96:97], v[100:101] op_sel:[0,1] op_sel_hi:[1,1]
	v_pk_mul_f32 v[48:49], v[44:45], v[102:103] op_sel_hi:[1,0]
	v_rcp_f32_e32 v52, v51
	s_add_u32 s14, s14, 0x1000
	s_addc_u32 s15, s15, 0
	v_fmac_f32_dpp v48, v38, v51 row_newbcast:8 row_mask:0xf bank_mask:0xf bound_ctrl:1
	v_fmac_f32_dpp v49, v38, v51 row_newbcast:12 row_mask:0xf bank_mask:0xf bound_ctrl:1
	s_cbranch_vccnz .Lgd2_rare0_1
.Lgd2_back0_1:
	v_cvt_pk_bf16_f32 v54, v48, v49
	v_pk_mul_f32 v[46:47], v[44:45], v[52:53] op_sel_hi:[1,0]
	v_pk_fma_f32 v[6:7], v[80:81], v[46:47], v[6:7] op_sel_hi:[0,1,1]
	v_pk_fma_f32 v[8:9], v[82:83], v[46:47], v[8:9] op_sel_hi:[0,1,1]
	v_pk_fma_f32 v[10:11], v[84:85], v[46:47], v[10:11] op_sel_hi:[0,1,1]
	v_pk_fma_f32 v[12:13], v[86:87], v[46:47], v[12:13] op_sel_hi:[0,1,1]
	v_pk_fma_f32 v[14:15], v[88:89], v[46:47], v[14:15] op_sel_hi:[0,1,1]
	v_pk_fma_f32 v[16:17], v[90:91], v[46:47], v[16:17] op_sel_hi:[0,1,1]
	v_pk_fma_f32 v[18:19], v[92:93], v[46:47], v[18:19] op_sel_hi:[0,1,1]
	v_pk_fma_f32 v[20:21], v[94:95], v[46:47], v[20:21] op_sel_hi:[0,1,1]
	global_store_dword v154, v54, s[14:15] offset:-4096
	s_waitcnt lgkmcnt(6)
	v_pk_mul_f32 v[38:39], v[6:7], v[126:127] op_sel_hi:[1,0]
	v_pk_mul_f32 v[40:41], v[6:7], v[126:127] op_sel:[0,1] op_sel_hi:[1,1]
	v_pk_fma_f32 v[38:39], v[8:9], v[128:129], v[38:39] op_sel_hi:[1,0,1]
	v_pk_fma_f32 v[40:41], v[8:9], v[128:129], v[40:41] op_sel:[0,1,0] op_sel_hi:[1,1,1]
	v_pk_fma_f32 v[38:39], v[10:11], v[130:131], v[38:39] op_sel_hi:[1,0,1]
	v_pk_fma_f32 v[40:41], v[10:11], v[130:131], v[40:41] op_sel:[0,1,0] op_sel_hi:[1,1,1]
	v_pk_fma_f32 v[38:39], v[12:13], v[132:133], v[38:39] op_sel_hi:[1,0,1]
	v_pk_fma_f32 v[40:41], v[12:13], v[132:133], v[40:41] op_sel:[0,1,0] op_sel_hi:[1,1,1]
	v_pk_fma_f32 v[38:39], v[14:15], v[134:135], v[38:39] op_sel_hi:[1,0,1]
	v_pk_fma_f32 v[40:41], v[14:15], v[134:135], v[40:41] op_sel:[0,1,0] op_sel_hi:[1,1,1]
	v_pk_fma_f32 v[38:39], v[16:17], v[136:137], v[38:39] op_sel_hi:[1,0,1]
	v_pk_fma_f32 v[40:41], v[16:17], v[136:137], v[40:41] op_sel:[0,1,0] op_sel_hi:[1,1,1]
	v_pk_fma_f32 v[38:39], v[18:19], v[138:139], v[38:39] op_sel_hi:[1,0,1]
	v_pk_fma_f32 v[40:41], v[18:19], v[138:139], v[40:41] op_sel:[0,1,0] op_sel_hi:[1,1,1]
	v_pk_fma_f32 v[38:39], v[20:21], v[140:141], v[38:39] op_sel_hi:[1,0,1]
	v_pk_fma_f32 v[40:41], v[20:21], v[140:141], v[40:41] op_sel:[0,1,0] op_sel_hi:[1,1,1]
	v_mul_f32_e32 v50, v144, v51
	v_add_f32_dpp v38, v38, v38 row_ror:8 row_mask:0xf bank_mask:0x3 bound_ctrl:1
	v_add_f32_dpp v39, v39, v39 row_ror:8 row_mask:0xf bank_mask:0x3 bound_ctrl:1
	v_add_f32_dpp v38, v40, v40 row_ror:8 row_mask:0xf bank_mask:0xc bound_ctrl:1
	v_add_f32_dpp v39, v41, v41 row_ror:8 row_mask:0xf bank_mask:0xc bound_ctrl:1
	ds_read_b128 v[80:83], v2 offset:4352
	v_add_f32_dpp v38, v38, v38 row_half_mirror row_mask:0xf bank_mask:0x5 bound_ctrl:1
	v_add_f32_dpp v38, v39, v39 row_half_mirror row_mask:0xf bank_mask:0xa bound_ctrl:1
	ds_read_b128 v[84:87], v2 offset:4608
	ds_read_b128 v[88:91], v2 offset:4864
	v_add_f32_dpp v38, v38, v38 quad_perm:[1,0,3,2] row_mask:0xf bank_mask:0xf bound_ctrl:1
	ds_read_b128 v[92:95], v2 offset:5120
	ds_read_b64 v[96:97], v3 offset:13568
	v_add_f32_dpp v38, v38, v38 quad_perm:[2,3,0,1] row_mask:0xf bank_mask:0xf bound_ctrl:1
	ds_read_b128 v[100:103], v1 offset:14656
	v_cmp_gt_f32_e32 vcc, 0x2b8cbccc, v50
	v_fmac_f32_dpp v142, -v38, v50 row_newbcast:0 row_mask:0xf bank_mask:0xf bound_ctrl:1
	v_fmac_f32_dpp v143, -v38, v50 row_newbcast:4 row_mask:0xf bank_mask:0xf bound_ctrl:1
	v_pk_mul_f32 v[44:45], v[142:143], v[144:145] op_sel:[0,1] op_sel_hi:[1,1]
	v_pk_mul_f32 v[48:49], v[44:45], v[146:147] op_sel_hi:[1,0]
	v_rcp_f32_e32 v52, v50
	s_add_u32 s14, s14, 0x1000
	s_addc_u32 s15, s15, 0
	v_fmac_f32_dpp v48, v38, v50 row_newbcast:8 row_mask:0xf bank_mask:0xf bound_ctrl:1
	v_fmac_f32_dpp v49, v38, v50 row_newbcast:12 row_mask:0xf bank_mask:0xf bound_ctrl:1
	s_cbranch_vccnz .Lgd2_rare0_2
.Lgd2_back0_2:
	v_cvt_pk_bf16_f32 v54, v48, v49
	v_pk_mul_f32 v[46:47], v[44:45], v[52:53] op_sel_hi:[1,0]
	v_pk_fma_f32 v[6:7], v[126:127], v[46:47], v[6:7] op_sel_hi:[0,1,1]
	v_pk_fma_f32 v[8:9], v[128:129], v[46:47], v[8:9] op_sel_hi:[0,1,1]
	v_pk_fma_f32 v[10:11], v[130:131], v[46:47], v[10:11] op_sel_hi:[0,1,1]
	v_pk_fma_f32 v[12:13], v[132:133], v[46:47], v[12:13] op_sel_hi:[0,1,1]
	v_pk_fma_f32 v[14:15], v[134:135], v[46:47], v[14:15] op_sel_hi:[0,1,1]
	v_pk_fma_f32 v[16:17], v[136:137], v[46:47], v[16:17] op_sel_hi:[0,1,1]
	v_pk_fma_f32 v[18:19], v[138:139], v[46:47], v[18:19] op_sel_hi:[0,1,1]
	v_pk_fma_f32 v[20:21], v[140:141], v[46:47], v[20:21] op_sel_hi:[0,1,1]
	global_store_dword v154, v54, s[14:15] offset:-4096
	s_waitcnt lgkmcnt(6)
	v_pk_mul_f32 v[38:39], v[6:7], v[56:57] op_sel_hi:[1,0]
	v_pk_mul_f32 v[40:41], v[6:7], v[56:57] op_sel:[0,1] op_sel_hi:[1,1]
	v_pk_fma_f32 v[38:39], v[8:9], v[58:59], v[38:39] op_sel_hi:[1,0,1]
	v_pk_fma_f32 v[40:41], v[8:9], v[58:59], v[40:41] op_sel:[0,1,0] op_sel_hi:[1,1,1]
	v_pk_fma_f32 v[38:39], v[10:11], v[60:61], v[38:39] op_sel_hi:[1,0,1]
	v_pk_fma_f32 v[40:41], v[10:11], v[60:61], v[40:41] op_sel:[0,1,0] op_sel_hi:[1,1,1]
	v_pk_fma_f32 v[38:39], v[12:13], v[62:63], v[38:39] op_sel_hi:[1,0,1]
	v_pk_fma_f32 v[40:41], v[12:13], v[62:63], v[40:41] op_sel:[0,1,0] op_sel_hi:[1,1,1]
	v_pk_fma_f32 v[38:39], v[14:15], v[64:65], v[38:39] op_sel_hi:[1,0,1]
	v_pk_fma_f32 v[40:41], v[14:15], v[64:65], v[40:41] op_sel:[0,1,0] op_sel_hi:[1,1,1]
	v_pk_fma_f32 v[38:39], v[16:17], v[66:67], v[38:39] op_sel_hi:[1,0,1]
	v_pk_fma_f32 v[40:41], v[16:17], v[66:67], v[40:41] op_sel:[0,1,0] op_sel_hi:[1,1,1]
	v_pk_fma_f32 v[38:39], v[18:19], v[68:69], v[38:39] op_sel_hi:[1,0,1]
	v_pk_fma_f32 v[40:41], v[18:19], v[68:69], v[40:41] op_sel:[0,1,0] op_sel_hi:[1,1,1]
	v_pk_fma_f32 v[38:39], v[20:21], v[70:71], v[38:39] op_sel_hi:[1,0,1]
	v_pk_fma_f32 v[40:41], v[20:21], v[70:71], v[40:41] op_sel:[0,1,0] op_sel_hi:[1,1,1]
	v_mul_f32_e32 v51, v76, v50
	v_add_f32_dpp v38, v38, v38 row_ror:8 row_mask:0xf bank_mask:0x3 bound_ctrl:1
	v_add_f32_dpp v39, v39, v39 row_ror:8 row_mask:0xf bank_mask:0x3 bound_ctrl:1
	v_add_f32_dpp v38, v40, v40 row_ror:8 row_mask:0xf bank_mask:0xc bound_ctrl:1
	v_add_f32_dpp v39, v41, v41 row_ror:8 row_mask:0xf bank_mask:0xc bound_ctrl:1
	ds_read_b128 v[126:129], v2 offset:5376
	v_add_f32_dpp v38, v38, v38 row_half_mirror row_mask:0xf bank_mask:0x5 bound_ctrl:1
	v_add_f32_dpp v38, v39, v39 row_half_mirror row_mask:0xf bank_mask:0xa bound_ctrl:1
	ds_read_b128 v[130:133], v2 offset:5632
	ds_read_b128 v[134:137], v2 offset:5888
	v_add_f32_dpp v38, v38, v38 quad_perm:[1,0,3,2] row_mask:0xf bank_mask:0xf bound_ctrl:1
	ds_read_b128 v[138:141], v2 offset:6144
	ds_read_b64 v[142:143], v3 offset:13824
	v_add_f32_dpp v38, v38, v38 quad_perm:[2,3,0,1] row_mask:0xf bank_mask:0xf bound_ctrl:1
	ds_read_b128 v[144:147], v1 offset:14672
	v_cmp_gt_f32_e32 vcc, 0x2b8cbccc, v51
	v_fmac_f32_dpp v72, -v38, v51 row_newbcast:0 row_mask:0xf bank_mask:0xf bound_ctrl:1
	v_fmac_f32_dpp v73, -v38, v51 row_newbcast:4 row_mask:0xf bank_mask:0xf bound_ctrl:1
	v_pk_mul_f32 v[44:45], v[72:73], v[76:77] op_sel:[0,1] op_sel_hi:[1,1]
	v_pk_mul_f32 v[48:49], v[44:45], v[78:79] op_sel_hi:[1,0]
	v_rcp_f32_e32 v52, v51
	s_add_u32 s14, s14, 0x1000
	s_addc_u32 s15, s15, 0
	v_fmac_f32_dpp v48, v38, v51 row_newbcast:8 row_mask:0xf bank_mask:0xf bound_ctrl:1
	v_fmac_f32_dpp v49, v38, v51 row_newbcast:12 row_mask:0xf bank_mask:0xf bound_ctrl:1
	s_cbranch_vccnz .Lgd2_rare0_3
.Lgd2_back0_3:
	v_cvt_pk_bf16_f32 v54, v48, v49
	v_pk_mul_f32 v[46:47], v[44:45], v[52:53] op_sel_hi:[1,0]
	v_pk_fma_f32 v[6:7], v[56:57], v[46:47], v[6:7] op_sel_hi:[0,1,1]
	v_pk_fma_f32 v[8:9], v[58:59], v[46:47], v[8:9] op_sel_hi:[0,1,1]
	v_pk_fma_f32 v[10:11], v[60:61], v[46:47], v[10:11] op_sel_hi:[0,1,1]
	v_pk_fma_f32 v[12:13], v[62:63], v[46:47], v[12:13] op_sel_hi:[0,1,1]
	v_pk_fma_f32 v[14:15], v[64:65], v[46:47], v[14:15] op_sel_hi:[0,1,1]
	v_pk_fma_f32 v[16:17], v[66:67], v[46:47], v[16:17] op_sel_hi:[0,1,1]
	v_pk_fma_f32 v[18:19], v[68:69], v[46:47], v[18:19] op_sel_hi:[0,1,1]
	v_pk_fma_f32 v[20:21], v[70:71], v[46:47], v[20:21] op_sel_hi:[0,1,1]
	global_store_dword v154, v54, s[14:15] offset:-4096
	s_waitcnt lgkmcnt(6)
	v_pk_mul_f32 v[38:39], v[6:7], v[80:81] op_sel_hi:[1,0]
	v_pk_mul_f32 v[40:41], v[6:7], v[80:81] op_sel:[0,1] op_sel_hi:[1,1]
	v_pk_fma_f32 v[38:39], v[8:9], v[82:83], v[38:39] op_sel_hi:[1,0,1]
	v_pk_fma_f32 v[40:41], v[8:9], v[82:83], v[40:41] op_sel:[0,1,0] op_sel_hi:[1,1,1]
	v_pk_fma_f32 v[38:39], v[10:11], v[84:85], v[38:39] op_sel_hi:[1,0,1]
	v_pk_fma_f32 v[40:41], v[10:11], v[84:85], v[40:41] op_sel:[0,1,0] op_sel_hi:[1,1,1]
	v_pk_fma_f32 v[38:39], v[12:13], v[86:87], v[38:39] op_sel_hi:[1,0,1]
	v_pk_fma_f32 v[40:41], v[12:13], v[86:87], v[40:41] op_sel:[0,1,0] op_sel_hi:[1,1,1]
	v_pk_fma_f32 v[38:39], v[14:15], v[88:89], v[38:39] op_sel_hi:[1,0,1]
	v_pk_fma_f32 v[40:41], v[14:15], v[88:89], v[40:41] op_sel:[0,1,0] op_sel_hi:[1,1,1]
	v_pk_fma_f32 v[38:39], v[16:17], v[90:91], v[38:39] op_sel_hi:[1,0,1]
	v_pk_fma_f32 v[40:41], v[16:17], v[90:91], v[40:41] op_sel:[0,1,0] op_sel_hi:[1,1,1]
	v_pk_fma_f32 v[38:39], v[18:19], v[92:93], v[38:39] op_sel_hi:[1,0,1]
	v_pk_fma_f32 v[40:41], v[18:19], v[92:93], v[40:41] op_sel:[0,1,0] op_sel_hi:[1,1,1]
	v_pk_fma_f32 v[38:39], v[20:21], v[94:95], v[38:39] op_sel_hi:[1,0,1]
	v_pk_fma_f32 v[40:41], v[20:21], v[94:95], v[40:41] op_sel:[0,1,0] op_sel_hi:[1,1,1]
	v_mul_f32_e32 v50, v100, v51
	v_add_f32_dpp v38, v38, v38 row_ror:8 row_mask:0xf bank_mask:0x3 bound_ctrl:1
	v_add_f32_dpp v39, v39, v39 row_ror:8 row_mask:0xf bank_mask:0x3 bound_ctrl:1
	v_add_f32_dpp v38, v40, v40 row_ror:8 row_mask:0xf bank_mask:0xc bound_ctrl:1
	v_add_f32_dpp v39, v41, v41 row_ror:8 row_mask:0xf bank_mask:0xc bound_ctrl:1
	ds_read_b128 v[56:59], v2 offset:6400
	v_add_f32_dpp v38, v38, v38 row_half_mirror row_mask:0xf bank_mask:0x5 bound_ctrl:1
	v_add_f32_dpp v38, v39, v39 row_half_mirror row_mask:0xf bank_mask:0xa bound_ctrl:1
	ds_read_b128 v[60:63], v2 offset:6656
	ds_read_b128 v[64:67], v2 offset:6912
	v_add_f32_dpp v38, v38, v38 quad_perm:[1,0,3,2] row_mask:0xf bank_mask:0xf bound_ctrl:1
	ds_read_b128 v[68:71], v2 offset:7168
	ds_read_b64 v[72:73], v3 offset:14080
	v_add_f32_dpp v38, v38, v38 quad_perm:[2,3,0,1] row_mask:0xf bank_mask:0xf bound_ctrl:1
	ds_read_b128 v[76:79], v1 offset:14688
	v_cmp_gt_f32_e32 vcc, 0x2b8cbccc, v50
	v_fmac_f32_dpp v96, -v38, v50 row_newbcast:0 row_mask:0xf bank_mask:0xf bound_ctrl:1
	v_fmac_f32_dpp v97, -v38, v50 row_newbcast:4 row_mask:0xf bank_mask:0xf bound_ctrl:1
	v_pk_mul_f32 v[44:45], v[96:97], v[100:101] op_sel:[0,1] op_sel_hi:[1,1]
	v_pk_mul_f32 v[48:49], v[44:45], v[102:103] op_sel_hi:[1,0]
	v_rcp_f32_e32 v52, v50
	s_add_u32 s14, s14, 0x1000
	s_addc_u32 s15, s15, 0
	v_fmac_f32_dpp v48, v38, v50 row_newbcast:8 row_mask:0xf bank_mask:0xf bound_ctrl:1
	v_fmac_f32_dpp v49, v38, v50 row_newbcast:12 row_mask:0xf bank_mask:0xf bound_ctrl:1
	s_cbranch_vccnz .Lgd2_rare0_4
.Lgd2_back0_4:
	v_cvt_pk_bf16_f32 v54, v48, v49
	v_pk_mul_f32 v[46:47], v[44:45], v[52:53] op_sel_hi:[1,0]
	v_pk_fma_f32 v[6:7], v[80:81], v[46:47], v[6:7] op_sel_hi:[0,1,1]
	v_pk_fma_f32 v[8:9], v[82:83], v[46:47], v[8:9] op_sel_hi:[0,1,1]
	v_pk_fma_f32 v[10:11], v[84:85], v[46:47], v[10:11] op_sel_hi:[0,1,1]
	v_pk_fma_f32 v[12:13], v[86:87], v[46:47], v[12:13] op_sel_hi:[0,1,1]
	v_pk_fma_f32 v[14:15], v[88:89], v[46:47], v[14:15] op_sel_hi:[0,1,1]
	v_pk_fma_f32 v[16:17], v[90:91], v[46:47], v[16:17] op_sel_hi:[0,1,1]
	v_pk_fma_f32 v[18:19], v[92:93], v[46:47], v[18:19] op_sel_hi:[0,1,1]
	v_pk_fma_f32 v[20:21], v[94:95], v[46:47], v[20:21] op_sel_hi:[0,1,1]
	global_store_dword v154, v54, s[14:15] offset:-4096
	s_waitcnt lgkmcnt(6)
	v_pk_mul_f32 v[38:39], v[6:7], v[126:127] op_sel_hi:[1,0]
	v_pk_mul_f32 v[40:41], v[6:7], v[126:127] op_sel:[0,1] op_sel_hi:[1,1]
	v_pk_fma_f32 v[38:39], v[8:9], v[128:129], v[38:39] op_sel_hi:[1,0,1]
	v_pk_fma_f32 v[40:41], v[8:9], v[128:129], v[40:41] op_sel:[0,1,0] op_sel_hi:[1,1,1]
	v_pk_fma_f32 v[38:39], v[10:11], v[130:131], v[38:39] op_sel_hi:[1,0,1]
	v_pk_fma_f32 v[40:41], v[10:11], v[130:131], v[40:41] op_sel:[0,1,0] op_sel_hi:[1,1,1]
	v_pk_fma_f32 v[38:39], v[12:13], v[132:133], v[38:39] op_sel_hi:[1,0,1]
	v_pk_fma_f32 v[40:41], v[12:13], v[132:133], v[40:41] op_sel:[0,1,0] op_sel_hi:[1,1,1]
	v_pk_fma_f32 v[38:39], v[14:15], v[134:135], v[38:39] op_sel_hi:[1,0,1]
	v_pk_fma_f32 v[40:41], v[14:15], v[134:135], v[40:41] op_sel:[0,1,0] op_sel_hi:[1,1,1]
	v_pk_fma_f32 v[38:39], v[16:17], v[136:137], v[38:39] op_sel_hi:[1,0,1]
	v_pk_fma_f32 v[40:41], v[16:17], v[136:137], v[40:41] op_sel:[0,1,0] op_sel_hi:[1,1,1]
	v_pk_fma_f32 v[38:39], v[18:19], v[138:139], v[38:39] op_sel_hi:[1,0,1]
	v_pk_fma_f32 v[40:41], v[18:19], v[138:139], v[40:41] op_sel:[0,1,0] op_sel_hi:[1,1,1]
	v_pk_fma_f32 v[38:39], v[20:21], v[140:141], v[38:39] op_sel_hi:[1,0,1]
	v_pk_fma_f32 v[40:41], v[20:21], v[140:141], v[40:41] op_sel:[0,1,0] op_sel_hi:[1,1,1]
	v_mul_f32_e32 v51, v144, v50
	v_add_f32_dpp v38, v38, v38 row_ror:8 row_mask:0xf bank_mask:0x3 bound_ctrl:1
	v_add_f32_dpp v39, v39, v39 row_ror:8 row_mask:0xf bank_mask:0x3 bound_ctrl:1
	v_add_f32_dpp v38, v40, v40 row_ror:8 row_mask:0xf bank_mask:0xc bound_ctrl:1
	v_add_f32_dpp v39, v41, v41 row_ror:8 row_mask:0xf bank_mask:0xc bound_ctrl:1
	ds_read_b128 v[80:83], v2 offset:7424
	v_add_f32_dpp v38, v38, v38 row_half_mirror row_mask:0xf bank_mask:0x5 bound_ctrl:1
	v_add_f32_dpp v38, v39, v39 row_half_mirror row_mask:0xf bank_mask:0xa bound_ctrl:1
	ds_read_b128 v[84:87], v2 offset:7680
	ds_read_b128 v[88:91], v2 offset:7936
	v_add_f32_dpp v38, v38, v38 quad_perm:[1,0,3,2] row_mask:0xf bank_mask:0xf bound_ctrl:1
	ds_read_b128 v[92:95], v2 offset:8192
	ds_read_b64 v[96:97], v3 offset:14336
	v_add_f32_dpp v38, v38, v38 quad_perm:[2,3,0,1] row_mask:0xf bank_mask:0xf bound_ctrl:1
	ds_read_b128 v[100:103], v1 offset:14704
	v_cmp_gt_f32_e32 vcc, 0x2b8cbccc, v51
	v_fmac_f32_dpp v142, -v38, v51 row_newbcast:0 row_mask:0xf bank_mask:0xf bound_ctrl:1
	v_fmac_f32_dpp v143, -v38, v51 row_newbcast:4 row_mask:0xf bank_mask:0xf bound_ctrl:1
	v_pk_mul_f32 v[44:45], v[142:143], v[144:145] op_sel:[0,1] op_sel_hi:[1,1]
	v_pk_mul_f32 v[48:49], v[44:45], v[146:147] op_sel_hi:[1,0]
	v_rcp_f32_e32 v52, v51
	s_add_u32 s14, s14, 0x1000
	s_addc_u32 s15, s15, 0
	v_fmac_f32_dpp v48, v38, v51 row_newbcast:8 row_mask:0xf bank_mask:0xf bound_ctrl:1
	v_fmac_f32_dpp v49, v38, v51 row_newbcast:12 row_mask:0xf bank_mask:0xf bound_ctrl:1
	s_cbranch_vccnz .Lgd2_rare0_5
.Lgd2_back0_5:
	v_cvt_pk_bf16_f32 v54, v48, v49
	v_pk_mul_f32 v[46:47], v[44:45], v[52:53] op_sel_hi:[1,0]
	v_pk_fma_f32 v[6:7], v[126:127], v[46:47], v[6:7] op_sel_hi:[0,1,1]
	v_pk_fma_f32 v[8:9], v[128:129], v[46:47], v[8:9] op_sel_hi:[0,1,1]
	v_pk_fma_f32 v[10:11], v[130:131], v[46:47], v[10:11] op_sel_hi:[0,1,1]
	v_pk_fma_f32 v[12:13], v[132:133], v[46:47], v[12:13] op_sel_hi:[0,1,1]
	v_pk_fma_f32 v[14:15], v[134:135], v[46:47], v[14:15] op_sel_hi:[0,1,1]
	v_pk_fma_f32 v[16:17], v[136:137], v[46:47], v[16:17] op_sel_hi:[0,1,1]
	v_pk_fma_f32 v[18:19], v[138:139], v[46:47], v[18:19] op_sel_hi:[0,1,1]
	v_pk_fma_f32 v[20:21], v[140:141], v[46:47], v[20:21] op_sel_hi:[0,1,1]
	global_store_dword v154, v54, s[14:15] offset:-4096
	s_waitcnt lgkmcnt(6)
	v_pk_mul_f32 v[38:39], v[6:7], v[56:57] op_sel_hi:[1,0]
	v_pk_mul_f32 v[40:41], v[6:7], v[56:57] op_sel:[0,1] op_sel_hi:[1,1]
	v_pk_fma_f32 v[38:39], v[8:9], v[58:59], v[38:39] op_sel_hi:[1,0,1]
	v_pk_fma_f32 v[40:41], v[8:9], v[58:59], v[40:41] op_sel:[0,1,0] op_sel_hi:[1,1,1]
	v_pk_fma_f32 v[38:39], v[10:11], v[60:61], v[38:39] op_sel_hi:[1,0,1]
	v_pk_fma_f32 v[40:41], v[10:11], v[60:61], v[40:41] op_sel:[0,1,0] op_sel_hi:[1,1,1]
	v_pk_fma_f32 v[38:39], v[12:13], v[62:63], v[38:39] op_sel_hi:[1,0,1]
	v_pk_fma_f32 v[40:41], v[12:13], v[62:63], v[40:41] op_sel:[0,1,0] op_sel_hi:[1,1,1]
	v_pk_fma_f32 v[38:39], v[14:15], v[64:65], v[38:39] op_sel_hi:[1,0,1]
	v_pk_fma_f32 v[40:41], v[14:15], v[64:65], v[40:41] op_sel:[0,1,0] op_sel_hi:[1,1,1]
	v_pk_fma_f32 v[38:39], v[16:17], v[66:67], v[38:39] op_sel_hi:[1,0,1]
	v_pk_fma_f32 v[40:41], v[16:17], v[66:67], v[40:41] op_sel:[0,1,0] op_sel_hi:[1,1,1]
	v_pk_fma_f32 v[38:39], v[18:19], v[68:69], v[38:39] op_sel_hi:[1,0,1]
	v_pk_fma_f32 v[40:41], v[18:19], v[68:69], v[40:41] op_sel:[0,1,0] op_sel_hi:[1,1,1]
	v_pk_fma_f32 v[38:39], v[20:21], v[70:71], v[38:39] op_sel_hi:[1,0,1]
	v_pk_fma_f32 v[40:41], v[20:21], v[70:71], v[40:41] op_sel:[0,1,0] op_sel_hi:[1,1,1]
	v_mul_f32_e32 v50, v76, v51
	v_add_f32_dpp v38, v38, v38 row_ror:8 row_mask:0xf bank_mask:0x3 bound_ctrl:1
	v_add_f32_dpp v39, v39, v39 row_ror:8 row_mask:0xf bank_mask:0x3 bound_ctrl:1
	v_add_f32_dpp v38, v40, v40 row_ror:8 row_mask:0xf bank_mask:0xc bound_ctrl:1
	v_add_f32_dpp v39, v41, v41 row_ror:8 row_mask:0xf bank_mask:0xc bound_ctrl:1
	ds_read_b128 v[126:129], v2 offset:16640
	v_add_f32_dpp v38, v38, v38 row_half_mirror row_mask:0xf bank_mask:0x5 bound_ctrl:1
	v_add_f32_dpp v38, v39, v39 row_half_mirror row_mask:0xf bank_mask:0xa bound_ctrl:1
	ds_read_b128 v[130:133], v2 offset:16896
	ds_read_b128 v[134:137], v2 offset:17152
	v_add_f32_dpp v38, v38, v38 quad_perm:[1,0,3,2] row_mask:0xf bank_mask:0xf bound_ctrl:1
	ds_read_b128 v[138:141], v2 offset:17408
	ds_read_b64 v[142:143], v3 offset:28928
	v_add_f32_dpp v38, v38, v38 quad_perm:[2,3,0,1] row_mask:0xf bank_mask:0xf bound_ctrl:1
	ds_read_b128 v[144:147], v1 offset:30976
	v_cmp_gt_f32_e32 vcc, 0x2b8cbccc, v50
	v_fmac_f32_dpp v72, -v38, v50 row_newbcast:0 row_mask:0xf bank_mask:0xf bound_ctrl:1
	v_fmac_f32_dpp v73, -v38, v50 row_newbcast:4 row_mask:0xf bank_mask:0xf bound_ctrl:1
	v_pk_mul_f32 v[44:45], v[72:73], v[76:77] op_sel:[0,1] op_sel_hi:[1,1]
	v_pk_mul_f32 v[48:49], v[44:45], v[78:79] op_sel_hi:[1,0]
	v_rcp_f32_e32 v52, v50
	s_add_u32 s14, s14, 0x1000
	s_addc_u32 s15, s15, 0
	v_fmac_f32_dpp v48, v38, v50 row_newbcast:8 row_mask:0xf bank_mask:0xf bound_ctrl:1
	v_fmac_f32_dpp v49, v38, v50 row_newbcast:12 row_mask:0xf bank_mask:0xf bound_ctrl:1
	s_cbranch_vccnz .Lgd2_rare0_6
.Lgd2_back0_6:
	v_cvt_pk_bf16_f32 v54, v48, v49
	v_pk_mul_f32 v[46:47], v[44:45], v[52:53] op_sel_hi:[1,0]
	v_pk_fma_f32 v[6:7], v[56:57], v[46:47], v[6:7] op_sel_hi:[0,1,1]
	v_pk_fma_f32 v[8:9], v[58:59], v[46:47], v[8:9] op_sel_hi:[0,1,1]
	v_pk_fma_f32 v[10:11], v[60:61], v[46:47], v[10:11] op_sel_hi:[0,1,1]
	v_pk_fma_f32 v[12:13], v[62:63], v[46:47], v[12:13] op_sel_hi:[0,1,1]
	v_pk_fma_f32 v[14:15], v[64:65], v[46:47], v[14:15] op_sel_hi:[0,1,1]
	v_pk_fma_f32 v[16:17], v[66:67], v[46:47], v[16:17] op_sel_hi:[0,1,1]
	v_pk_fma_f32 v[18:19], v[68:69], v[46:47], v[18:19] op_sel_hi:[0,1,1]
	v_pk_fma_f32 v[20:21], v[70:71], v[46:47], v[20:21] op_sel_hi:[0,1,1]
	global_store_dword v154, v54, s[14:15] offset:-4096
	s_waitcnt lgkmcnt(6)
	v_pk_mul_f32 v[38:39], v[6:7], v[80:81] op_sel_hi:[1,0]
	v_pk_mul_f32 v[40:41], v[6:7], v[80:81] op_sel:[0,1] op_sel_hi:[1,1]
	v_pk_fma_f32 v[38:39], v[8:9], v[82:83], v[38:39] op_sel_hi:[1,0,1]
	v_pk_fma_f32 v[40:41], v[8:9], v[82:83], v[40:41] op_sel:[0,1,0] op_sel_hi:[1,1,1]
	v_pk_fma_f32 v[38:39], v[10:11], v[84:85], v[38:39] op_sel_hi:[1,0,1]
	v_pk_fma_f32 v[40:41], v[10:11], v[84:85], v[40:41] op_sel:[0,1,0] op_sel_hi:[1,1,1]
	v_pk_fma_f32 v[38:39], v[12:13], v[86:87], v[38:39] op_sel_hi:[1,0,1]
	v_pk_fma_f32 v[40:41], v[12:13], v[86:87], v[40:41] op_sel:[0,1,0] op_sel_hi:[1,1,1]
	v_pk_fma_f32 v[38:39], v[14:15], v[88:89], v[38:39] op_sel_hi:[1,0,1]
	v_pk_fma_f32 v[40:41], v[14:15], v[88:89], v[40:41] op_sel:[0,1,0] op_sel_hi:[1,1,1]
	v_pk_fma_f32 v[38:39], v[16:17], v[90:91], v[38:39] op_sel_hi:[1,0,1]
	v_pk_fma_f32 v[40:41], v[16:17], v[90:91], v[40:41] op_sel:[0,1,0] op_sel_hi:[1,1,1]
	v_pk_fma_f32 v[38:39], v[18:19], v[92:93], v[38:39] op_sel_hi:[1,0,1]
	v_pk_fma_f32 v[40:41], v[18:19], v[92:93], v[40:41] op_sel:[0,1,0] op_sel_hi:[1,1,1]
	v_pk_fma_f32 v[38:39], v[20:21], v[94:95], v[38:39] op_sel_hi:[1,0,1]
	v_pk_fma_f32 v[40:41], v[20:21], v[94:95], v[40:41] op_sel:[0,1,0] op_sel_hi:[1,1,1]
	v_mul_f32_e32 v51, v100, v50
	v_add_f32_dpp v38, v38, v38 row_ror:8 row_mask:0xf bank_mask:0x3 bound_ctrl:1
	v_add_f32_dpp v39, v39, v39 row_ror:8 row_mask:0xf bank_mask:0x3 bound_ctrl:1
	v_add_f32_dpp v38, v40, v40 row_ror:8 row_mask:0xf bank_mask:0xc bound_ctrl:1
	v_add_f32_dpp v39, v41, v41 row_ror:8 row_mask:0xf bank_mask:0xc bound_ctrl:1
	ds_read_b128 v[56:59], v2 offset:17664
	v_add_f32_dpp v38, v38, v38 row_half_mirror row_mask:0xf bank_mask:0x5 bound_ctrl:1
	v_add_f32_dpp v38, v39, v39 row_half_mirror row_mask:0xf bank_mask:0xa bound_ctrl:1
	ds_read_b128 v[60:63], v2 offset:17920
	ds_read_b128 v[64:67], v2 offset:18176
	v_add_f32_dpp v38, v38, v38 quad_perm:[1,0,3,2] row_mask:0xf bank_mask:0xf bound_ctrl:1
	ds_read_b128 v[68:71], v2 offset:18432
	ds_read_b64 v[72:73], v3 offset:29184
	v_add_f32_dpp v38, v38, v38 quad_perm:[2,3,0,1] row_mask:0xf bank_mask:0xf bound_ctrl:1
	ds_read_b128 v[76:79], v1 offset:30992
	v_cmp_gt_f32_e32 vcc, 0x2b8cbccc, v51
	v_fmac_f32_dpp v96, -v38, v51 row_newbcast:0 row_mask:0xf bank_mask:0xf bound_ctrl:1
	v_fmac_f32_dpp v97, -v38, v51 row_newbcast:4 row_mask:0xf bank_mask:0xf bound_ctrl:1
	v_pk_mul_f32 v[44:45], v[96:97], v[100:101] op_sel:[0,1] op_sel_hi:[1,1]
	v_pk_mul_f32 v[48:49], v[44:45], v[102:103] op_sel_hi:[1,0]
	v_rcp_f32_e32 v52, v51
	s_add_u32 s14, s14, 0x1000
	s_addc_u32 s15, s15, 0
	v_fmac_f32_dpp v48, v38, v51 row_newbcast:8 row_mask:0xf bank_mask:0xf bound_ctrl:1
	v_fmac_f32_dpp v49, v38, v51 row_newbcast:12 row_mask:0xf bank_mask:0xf bound_ctrl:1
	s_cbranch_vccnz .Lgd2_rare0_7
.Lgd2_back0_7:
	v_cvt_pk_bf16_f32 v54, v48, v49
	v_pk_mul_f32 v[46:47], v[44:45], v[52:53] op_sel_hi:[1,0]
	v_pk_fma_f32 v[6:7], v[80:81], v[46:47], v[6:7] op_sel_hi:[0,1,1]
	v_pk_fma_f32 v[8:9], v[82:83], v[46:47], v[8:9] op_sel_hi:[0,1,1]
	v_pk_fma_f32 v[10:11], v[84:85], v[46:47], v[10:11] op_sel_hi:[0,1,1]
	v_pk_fma_f32 v[12:13], v[86:87], v[46:47], v[12:13] op_sel_hi:[0,1,1]
	v_pk_fma_f32 v[14:15], v[88:89], v[46:47], v[14:15] op_sel_hi:[0,1,1]
	v_pk_fma_f32 v[16:17], v[90:91], v[46:47], v[16:17] op_sel_hi:[0,1,1]
	v_pk_fma_f32 v[18:19], v[92:93], v[46:47], v[18:19] op_sel_hi:[0,1,1]
	v_pk_fma_f32 v[20:21], v[94:95], v[46:47], v[20:21] op_sel_hi:[0,1,1]
	global_store_dword v154, v54, s[14:15] offset:-4096
	s_waitcnt vmcnt(8)
	v_lshlrev_b32_e32 v116, 16, v108
	v_lshlrev_b32_e32 v117, 16, v109
	v_and_b32_e32 v118, s17, v108
	v_and_b32_e32 v119, s17, v109
	v_lshlrev_b32_e32 v120, 16, v110
	v_and_b32_e32 v121, s17, v110
	v_lshlrev_b32_e32 v122, 16, v111
	v_and_b32_e32 v123, s17, v111
	v_lshlrev_b32_e32 v124, 16, v112
	v_and_b32_e32 v125, s17, v112
	ds_write_b128 v32, v[116:119] offset:33024
	ds_write_b64 v33, v[120:121] offset:33024
	ds_write_b64 v34, v[122:123] offset:33024
	ds_write_b64 v34, v[124:125] offset:33152
	ds_write_b32 v35, v113 offset:33024
	s_add_i32 s16, s16, 8
	s_waitcnt lgkmcnt(0)
	s_barrier
	s_cmpk_lt_u32 s16, 0x800
	s_cbranch_scc0 .Lgd2_done
	global_load_dword v108, v36, s[8:9]
	global_load_dword v109, v36, s[8:9] offset:-2048
	global_load_dword v111, v104, s[8:9] offset:2048
	global_load_dword v110, v37, s[10:11]
	global_load_dword v112, v105, s[10:11]
	global_load_dword v113, v106, s[12:13]
	s_add_u32 s8, s8, 0xc000
	s_addc_u32 s9, s9, 0
	s_add_u32 s10, s10, 0x20000
	s_addc_u32 s11, s11, 0
	s_add_u32 s12, s12, 0x400
	s_addc_u32 s13, s13, 0
	s_waitcnt lgkmcnt(6)
	v_pk_mul_f32 v[38:39], v[6:7], v[126:127] op_sel_hi:[1,0]
	v_pk_mul_f32 v[40:41], v[6:7], v[126:127] op_sel:[0,1] op_sel_hi:[1,1]
	v_pk_fma_f32 v[38:39], v[8:9], v[128:129], v[38:39] op_sel_hi:[1,0,1]
	v_pk_fma_f32 v[40:41], v[8:9], v[128:129], v[40:41] op_sel:[0,1,0] op_sel_hi:[1,1,1]
	v_pk_fma_f32 v[38:39], v[10:11], v[130:131], v[38:39] op_sel_hi:[1,0,1]
	v_pk_fma_f32 v[40:41], v[10:11], v[130:131], v[40:41] op_sel:[0,1,0] op_sel_hi:[1,1,1]
	v_pk_fma_f32 v[38:39], v[12:13], v[132:133], v[38:39] op_sel_hi:[1,0,1]
	v_pk_fma_f32 v[40:41], v[12:13], v[132:133], v[40:41] op_sel:[0,1,0] op_sel_hi:[1,1,1]
	v_pk_fma_f32 v[38:39], v[14:15], v[134:135], v[38:39] op_sel_hi:[1,0,1]
	v_pk_fma_f32 v[40:41], v[14:15], v[134:135], v[40:41] op_sel:[0,1,0] op_sel_hi:[1,1,1]
	v_pk_fma_f32 v[38:39], v[16:17], v[136:137], v[38:39] op_sel_hi:[1,0,1]
	v_pk_fma_f32 v[40:41], v[16:17], v[136:137], v[40:41] op_sel:[0,1,0] op_sel_hi:[1,1,1]
	v_pk_fma_f32 v[38:39], v[18:19], v[138:139], v[38:39] op_sel_hi:[1,0,1]
	v_pk_fma_f32 v[40:41], v[18:19], v[138:139], v[40:41] op_sel:[0,1,0] op_sel_hi:[1,1,1]
	v_pk_fma_f32 v[38:39], v[20:21], v[140:141], v[38:39] op_sel_hi:[1,0,1]
	v_pk_fma_f32 v[40:41], v[20:21], v[140:141], v[40:41] op_sel:[0,1,0] op_sel_hi:[1,1,1]
	v_mul_f32_e32 v50, v144, v51
	v_add_f32_dpp v38, v38, v38 row_ror:8 row_mask:0xf bank_mask:0x3 bound_ctrl:1
	v_add_f32_dpp v39, v39, v39 row_ror:8 row_mask:0xf bank_mask:0x3 bound_ctrl:1
	v_add_f32_dpp v38, v40, v40 row_ror:8 row_mask:0xf bank_mask:0xc bound_ctrl:1
	v_add_f32_dpp v39, v41, v41 row_ror:8 row_mask:0xf bank_mask:0xc bound_ctrl:1
	ds_read_b128 v[80:83], v2 offset:18688
	v_add_f32_dpp v38, v38, v38 row_half_mirror row_mask:0xf bank_mask:0x5 bound_ctrl:1
	v_add_f32_dpp v38, v39, v39 row_half_mirror row_mask:0xf bank_mask:0xa bound_ctrl:1
	ds_read_b128 v[84:87], v2 offset:18944
	ds_read_b128 v[88:91], v2 offset:19200
	v_add_f32_dpp v38, v38, v38 quad_perm:[1,0,3,2] row_mask:0xf bank_mask:0xf bound_ctrl:1
	ds_read_b128 v[92:95], v2 offset:19456
	ds_read_b64 v[96:97], v3 offset:29440
	v_add_f32_dpp v38, v38, v38 quad_perm:[2,3,0,1] row_mask:0xf bank_mask:0xf bound_ctrl:1
	ds_read_b128 v[100:103], v1 offset:31008
	v_cmp_gt_f32_e32 vcc, 0x2b8cbccc, v50
	v_fmac_f32_dpp v142, -v38, v50 row_newbcast:0 row_mask:0xf bank_mask:0xf bound_ctrl:1
	v_fmac_f32_dpp v143, -v38, v50 row_newbcast:4 row_mask:0xf bank_mask:0xf bound_ctrl:1
	v_pk_mul_f32 v[44:45], v[142:143], v[144:145] op_sel:[0,1] op_sel_hi:[1,1]
	v_pk_mul_f32 v[48:49], v[44:45], v[146:147] op_sel_hi:[1,0]
	v_rcp_f32_e32 v52, v50
	s_add_u32 s14, s14, 0x1000
	s_addc_u32 s15, s15, 0
	v_fmac_f32_dpp v48, v38, v50 row_newbcast:8 row_mask:0xf bank_mask:0xf bound_ctrl:1
	v_fmac_f32_dpp v49, v38, v50 row_newbcast:12 row_mask:0xf bank_mask:0xf bound_ctrl:1
	s_cbranch_vccnz .Lgd2_rare1_0
.Lgd2_back1_0:
	v_cvt_pk_bf16_f32 v54, v48, v49
	v_pk_mul_f32 v[46:47], v[44:45], v[52:53] op_sel_hi:[1,0]
	v_pk_fma_f32 v[6:7], v[126:127], v[46:47], v[6:7] op_sel_hi:[0,1,1]
	v_pk_fma_f32 v[8:9], v[128:129], v[46:47], v[8:9] op_sel_hi:[0,1,1]
	v_pk_fma_f32 v[10:11], v[130:131], v[46:47], v[10:11] op_sel_hi:[0,1,1]
	v_pk_fma_f32 v[12:13], v[132:133], v[46:47], v[12:13] op_sel_hi:[0,1,1]
	v_pk_fma_f32 v[14:15], v[134:135], v[46:47], v[14:15] op_sel_hi:[0,1,1]
	v_pk_fma_f32 v[16:17], v[136:137], v[46:47], v[16:17] op_sel_hi:[0,1,1]
	v_pk_fma_f32 v[18:19], v[138:139], v[46:47], v[18:19] op_sel_hi:[0,1,1]
	v_pk_fma_f32 v[20:21], v[140:141], v[46:47], v[20:21] op_sel_hi:[0,1,1]
	global_store_dword v154, v54, s[14:15] offset:-4096
	s_waitcnt lgkmcnt(6)
	v_pk_mul_f32 v[38:39], v[6:7], v[56:57] op_sel_hi:[1,0]
	v_pk_mul_f32 v[40:41], v[6:7], v[56:57] op_sel:[0,1] op_sel_hi:[1,1]
	v_pk_fma_f32 v[38:39], v[8:9], v[58:59], v[38:39] op_sel_hi:[1,0,1]
	v_pk_fma_f32 v[40:41], v[8:9], v[58:59], v[40:41] op_sel:[0,1,0] op_sel_hi:[1,1,1]
	v_pk_fma_f32 v[38:39], v[10:11], v[60:61], v[38:39] op_sel_hi:[1,0,1]
	v_pk_fma_f32 v[40:41], v[10:11], v[60:61], v[40:41] op_sel:[0,1,0] op_sel_hi:[1,1,1]
	v_pk_fma_f32 v[38:39], v[12:13], v[62:63], v[38:39] op_sel_hi:[1,0,1]
	v_pk_fma_f32 v[40:41], v[12:13], v[62:63], v[40:41] op_sel:[0,1,0] op_sel_hi:[1,1,1]
	v_pk_fma_f32 v[38:39], v[14:15], v[64:65], v[38:39] op_sel_hi:[1,0,1]
	v_pk_fma_f32 v[40:41], v[14:15], v[64:65], v[40:41] op_sel:[0,1,0] op_sel_hi:[1,1,1]
	v_pk_fma_f32 v[38:39], v[16:17], v[66:67], v[38:39] op_sel_hi:[1,0,1]
	v_pk_fma_f32 v[40:41], v[16:17], v[66:67], v[40:41] op_sel:[0,1,0] op_sel_hi:[1,1,1]
	v_pk_fma_f32 v[38:39], v[18:19], v[68:69], v[38:39] op_sel_hi:[1,0,1]
	v_pk_fma_f32 v[40:41], v[18:19], v[68:69], v[40:41] op_sel:[0,1,0] op_sel_hi:[1,1,1]
	v_pk_fma_f32 v[38:39], v[20:21], v[70:71], v[38:39] op_sel_hi:[1,0,1]
	v_pk_fma_f32 v[40:41], v[20:21], v[70:71], v[40:41] op_sel:[0,1,0] op_sel_hi:[1,1,1]
	v_mul_f32_e32 v51, v76, v50
	v_add_f32_dpp v38, v38, v38 row_ror:8 row_mask:0xf bank_mask:0x3 bound_ctrl:1
	v_add_f32_dpp v39, v39, v39 row_ror:8 row_mask:0xf bank_mask:0x3 bound_ctrl:1
	v_add_f32_dpp v38, v40, v40 row_ror:8 row_mask:0xf bank_mask:0xc bound_ctrl:1
	v_add_f32_dpp v39, v41, v41 row_ror:8 row_mask:0xf bank_mask:0xc bound_ctrl:1
	ds_read_b128 v[126:129], v2 offset:19712
	v_add_f32_dpp v38, v38, v38 row_half_mirror row_mask:0xf bank_mask:0x5 bound_ctrl:1
	v_add_f32_dpp v38, v39, v39 row_half_mirror row_mask:0xf bank_mask:0xa bound_ctrl:1
	ds_read_b128 v[130:133], v2 offset:19968
	ds_read_b128 v[134:137], v2 offset:20224
	v_add_f32_dpp v38, v38, v38 quad_perm:[1,0,3,2] row_mask:0xf bank_mask:0xf bound_ctrl:1
	ds_read_b128 v[138:141], v2 offset:20480
	ds_read_b64 v[142:143], v3 offset:29696
	v_add_f32_dpp v38, v38, v38 quad_perm:[2,3,0,1] row_mask:0xf bank_mask:0xf bound_ctrl:1
	ds_read_b128 v[144:147], v1 offset:31024
	v_cmp_gt_f32_e32 vcc, 0x2b8cbccc, v51
	v_fmac_f32_dpp v72, -v38, v51 row_newbcast:0 row_mask:0xf bank_mask:0xf bound_ctrl:1
	v_fmac_f32_dpp v73, -v38, v51 row_newbcast:4 row_mask:0xf bank_mask:0xf bound_ctrl:1
	v_pk_mul_f32 v[44:45], v[72:73], v[76:77] op_sel:[0,1] op_sel_hi:[1,1]
	v_pk_mul_f32 v[48:49], v[44:45], v[78:79] op_sel_hi:[1,0]
	v_rcp_f32_e32 v52, v51
	s_add_u32 s14, s14, 0x1000
	s_addc_u32 s15, s15, 0
	v_fmac_f32_dpp v48, v38, v51 row_newbcast:8 row_mask:0xf bank_mask:0xf bound_ctrl:1
	v_fmac_f32_dpp v49, v38, v51 row_newbcast:12 row_mask:0xf bank_mask:0xf bound_ctrl:1
	s_cbranch_vccnz .Lgd2_rare1_1
.Lgd2_back1_1:
	v_cvt_pk_bf16_f32 v54, v48, v49
	v_pk_mul_f32 v[46:47], v[44:45], v[52:53] op_sel_hi:[1,0]
	v_pk_fma_f32 v[6:7], v[56:57], v[46:47], v[6:7] op_sel_hi:[0,1,1]
	v_pk_fma_f32 v[8:9], v[58:59], v[46:47], v[8:9] op_sel_hi:[0,1,1]
	v_pk_fma_f32 v[10:11], v[60:61], v[46:47], v[10:11] op_sel_hi:[0,1,1]
	v_pk_fma_f32 v[12:13], v[62:63], v[46:47], v[12:13] op_sel_hi:[0,1,1]
	v_pk_fma_f32 v[14:15], v[64:65], v[46:47], v[14:15] op_sel_hi:[0,1,1]
	v_pk_fma_f32 v[16:17], v[66:67], v[46:47], v[16:17] op_sel_hi:[0,1,1]
	v_pk_fma_f32 v[18:19], v[68:69], v[46:47], v[18:19] op_sel_hi:[0,1,1]
	v_pk_fma_f32 v[20:21], v[70:71], v[46:47], v[20:21] op_sel_hi:[0,1,1]
	global_store_dword v154, v54, s[14:15] offset:-4096
	s_waitcnt lgkmcnt(6)
	v_pk_mul_f32 v[38:39], v[6:7], v[80:81] op_sel_hi:[1,0]
	v_pk_mul_f32 v[40:41], v[6:7], v[80:81] op_sel:[0,1] op_sel_hi:[1,1]
	v_pk_fma_f32 v[38:39], v[8:9], v[82:83], v[38:39] op_sel_hi:[1,0,1]
	v_pk_fma_f32 v[40:41], v[8:9], v[82:83], v[40:41] op_sel:[0,1,0] op_sel_hi:[1,1,1]
	v_pk_fma_f32 v[38:39], v[10:11], v[84:85], v[38:39] op_sel_hi:[1,0,1]
	v_pk_fma_f32 v[40:41], v[10:11], v[84:85], v[40:41] op_sel:[0,1,0] op_sel_hi:[1,1,1]
	v_pk_fma_f32 v[38:39], v[12:13], v[86:87], v[38:39] op_sel_hi:[1,0,1]
	v_pk_fma_f32 v[40:41], v[12:13], v[86:87], v[40:41] op_sel:[0,1,0] op_sel_hi:[1,1,1]
	v_pk_fma_f32 v[38:39], v[14:15], v[88:89], v[38:39] op_sel_hi:[1,0,1]
	v_pk_fma_f32 v[40:41], v[14:15], v[88:89], v[40:41] op_sel:[0,1,0] op_sel_hi:[1,1,1]
	v_pk_fma_f32 v[38:39], v[16:17], v[90:91], v[38:39] op_sel_hi:[1,0,1]
	v_pk_fma_f32 v[40:41], v[16:17], v[90:91], v[40:41] op_sel:[0,1,0] op_sel_hi:[1,1,1]
	v_pk_fma_f32 v[38:39], v[18:19], v[92:93], v[38:39] op_sel_hi:[1,0,1]
	v_pk_fma_f32 v[40:41], v[18:19], v[92:93], v[40:41] op_sel:[0,1,0] op_sel_hi:[1,1,1]
	v_pk_fma_f32 v[38:39], v[20:21], v[94:95], v[38:39] op_sel_hi:[1,0,1]
	v_pk_fma_f32 v[40:41], v[20:21], v[94:95], v[40:41] op_sel:[0,1,0] op_sel_hi:[1,1,1]
	v_mul_f32_e32 v50, v100, v51
	v_add_f32_dpp v38, v38, v38 row_ror:8 row_mask:0xf bank_mask:0x3 bound_ctrl:1
	v_add_f32_dpp v39, v39, v39 row_ror:8 row_mask:0xf bank_mask:0x3 bound_ctrl:1
	v_add_f32_dpp v38, v40, v40 row_ror:8 row_mask:0xf bank_mask:0xc bound_ctrl:1
	v_add_f32_dpp v39, v41, v41 row_ror:8 row_mask:0xf bank_mask:0xc bound_ctrl:1
	ds_read_b128 v[56:59], v2 offset:20736
	v_add_f32_dpp v38, v38, v38 row_half_mirror row_mask:0xf bank_mask:0x5 bound_ctrl:1
	v_add_f32_dpp v38, v39, v39 row_half_mirror row_mask:0xf bank_mask:0xa bound_ctrl:1
	ds_read_b128 v[60:63], v2 offset:20992
	ds_read_b128 v[64:67], v2 offset:21248
	v_add_f32_dpp v38, v38, v38 quad_perm:[1,0,3,2] row_mask:0xf bank_mask:0xf bound_ctrl:1
	ds_read_b128 v[68:71], v2 offset:21504
	ds_read_b64 v[72:73], v3 offset:29952
	v_add_f32_dpp v38, v38, v38 quad_perm:[2,3,0,1] row_mask:0xf bank_mask:0xf bound_ctrl:1
	ds_read_b128 v[76:79], v1 offset:31040
	v_cmp_gt_f32_e32 vcc, 0x2b8cbccc, v50
	v_fmac_f32_dpp v96, -v38, v50 row_newbcast:0 row_mask:0xf bank_mask:0xf bound_ctrl:1
	v_fmac_f32_dpp v97, -v38, v50 row_newbcast:4 row_mask:0xf bank_mask:0xf bound_ctrl:1
	v_pk_mul_f32 v[44:45], v[96:97], v[100:101] op_sel:[0,1] op_sel_hi:[1,1]
	v_pk_mul_f32 v[48:49], v[44:45], v[102:103] op_sel_hi:[1,0]
	v_rcp_f32_e32 v52, v50
	s_add_u32 s14, s14, 0x1000
	s_addc_u32 s15, s15, 0
	v_fmac_f32_dpp v48, v38, v50 row_newbcast:8 row_mask:0xf bank_mask:0xf bound_ctrl:1
	v_fmac_f32_dpp v49, v38, v50 row_newbcast:12 row_mask:0xf bank_mask:0xf bound_ctrl:1
	s_cbranch_vccnz .Lgd2_rare1_2
.Lgd2_back1_2:
	v_cvt_pk_bf16_f32 v54, v48, v49
	v_pk_mul_f32 v[46:47], v[44:45], v[52:53] op_sel_hi:[1,0]
	v_pk_fma_f32 v[6:7], v[80:81], v[46:47], v[6:7] op_sel_hi:[0,1,1]
	v_pk_fma_f32 v[8:9], v[82:83], v[46:47], v[8:9] op_sel_hi:[0,1,1]
	v_pk_fma_f32 v[10:11], v[84:85], v[46:47], v[10:11] op_sel_hi:[0,1,1]
	v_pk_fma_f32 v[12:13], v[86:87], v[46:47], v[12:13] op_sel_hi:[0,1,1]
	v_pk_fma_f32 v[14:15], v[88:89], v[46:47], v[14:15] op_sel_hi:[0,1,1]
	v_pk_fma_f32 v[16:17], v[90:91], v[46:47], v[16:17] op_sel_hi:[0,1,1]
	v_pk_fma_f32 v[18:19], v[92:93], v[46:47], v[18:19] op_sel_hi:[0,1,1]
	v_pk_fma_f32 v[20:21], v[94:95], v[46:47], v[20:21] op_sel_hi:[0,1,1]
	global_store_dword v154, v54, s[14:15] offset:-4096
	s_waitcnt lgkmcnt(6)
	v_pk_mul_f32 v[38:39], v[6:7], v[126:127] op_sel_hi:[1,0]
	v_pk_mul_f32 v[40:41], v[6:7], v[126:127] op_sel:[0,1] op_sel_hi:[1,1]
	v_pk_fma_f32 v[38:39], v[8:9], v[128:129], v[38:39] op_sel_hi:[1,0,1]
	v_pk_fma_f32 v[40:41], v[8:9], v[128:129], v[40:41] op_sel:[0,1,0] op_sel_hi:[1,1,1]
	v_pk_fma_f32 v[38:39], v[10:11], v[130:131], v[38:39] op_sel_hi:[1,0,1]
	v_pk_fma_f32 v[40:41], v[10:11], v[130:131], v[40:41] op_sel:[0,1,0] op_sel_hi:[1,1,1]
	v_pk_fma_f32 v[38:39], v[12:13], v[132:133], v[38:39] op_sel_hi:[1,0,1]
	v_pk_fma_f32 v[40:41], v[12:13], v[132:133], v[40:41] op_sel:[0,1,0] op_sel_hi:[1,1,1]
	v_pk_fma_f32 v[38:39], v[14:15], v[134:135], v[38:39] op_sel_hi:[1,0,1]
	v_pk_fma_f32 v[40:41], v[14:15], v[134:135], v[40:41] op_sel:[0,1,0] op_sel_hi:[1,1,1]
	v_pk_fma_f32 v[38:39], v[16:17], v[136:137], v[38:39] op_sel_hi:[1,0,1]
	v_pk_fma_f32 v[40:41], v[16:17], v[136:137], v[40:41] op_sel:[0,1,0] op_sel_hi:[1,1,1]
	v_pk_fma_f32 v[38:39], v[18:19], v[138:139], v[38:39] op_sel_hi:[1,0,1]
	v_pk_fma_f32 v[40:41], v[18:19], v[138:139], v[40:41] op_sel:[0,1,0] op_sel_hi:[1,1,1]
	v_pk_fma_f32 v[38:39], v[20:21], v[140:141], v[38:39] op_sel_hi:[1,0,1]
	v_pk_fma_f32 v[40:41], v[20:21], v[140:141], v[40:41] op_sel:[0,1,0] op_sel_hi:[1,1,1]
	v_mul_f32_e32 v51, v144, v50
	v_add_f32_dpp v38, v38, v38 row_ror:8 row_mask:0xf bank_mask:0x3 bound_ctrl:1
	v_add_f32_dpp v39, v39, v39 row_ror:8 row_mask:0xf bank_mask:0x3 bound_ctrl:1
	v_add_f32_dpp v38, v40, v40 row_ror:8 row_mask:0xf bank_mask:0xc bound_ctrl:1
	v_add_f32_dpp v39, v41, v41 row_ror:8 row_mask:0xf bank_mask:0xc bound_ctrl:1
	ds_read_b128 v[80:83], v2 offset:21760
	v_add_f32_dpp v38, v38, v38 row_half_mirror row_mask:0xf bank_mask:0x5 bound_ctrl:1
	v_add_f32_dpp v38, v39, v39 row_half_mirror row_mask:0xf bank_mask:0xa bound_ctrl:1
	ds_read_b128 v[84:87], v2 offset:22016
	ds_read_b128 v[88:91], v2 offset:22272
	v_add_f32_dpp v38, v38, v38 quad_perm:[1,0,3,2] row_mask:0xf bank_mask:0xf bound_ctrl:1
	ds_read_b128 v[92:95], v2 offset:22528
	ds_read_b64 v[96:97], v3 offset:30208
	v_add_f32_dpp v38, v38, v38 quad_perm:[2,3,0,1] row_mask:0xf bank_mask:0xf bound_ctrl:1
	ds_read_b128 v[100:103], v1 offset:31056
	v_cmp_gt_f32_e32 vcc, 0x2b8cbccc, v51
	v_fmac_f32_dpp v142, -v38, v51 row_newbcast:0 row_mask:0xf bank_mask:0xf bound_ctrl:1
	v_fmac_f32_dpp v143, -v38, v51 row_newbcast:4 row_mask:0xf bank_mask:0xf bound_ctrl:1
	v_pk_mul_f32 v[44:45], v[142:143], v[144:145] op_sel:[0,1] op_sel_hi:[1,1]
	v_pk_mul_f32 v[48:49], v[44:45], v[146:147] op_sel_hi:[1,0]
	v_rcp_f32_e32 v52, v51
	s_add_u32 s14, s14, 0x1000
	s_addc_u32 s15, s15, 0
	v_fmac_f32_dpp v48, v38, v51 row_newbcast:8 row_mask:0xf bank_mask:0xf bound_ctrl:1
	v_fmac_f32_dpp v49, v38, v51 row_newbcast:12 row_mask:0xf bank_mask:0xf bound_ctrl:1
	s_cbranch_vccnz .Lgd2_rare1_3
.Lgd2_back1_3:
	v_cvt_pk_bf16_f32 v54, v48, v49
	v_pk_mul_f32 v[46:47], v[44:45], v[52:53] op_sel_hi:[1,0]
	v_pk_fma_f32 v[6:7], v[126:127], v[46:47], v[6:7] op_sel_hi:[0,1,1]
	v_pk_fma_f32 v[8:9], v[128:129], v[46:47], v[8:9] op_sel_hi:[0,1,1]
	v_pk_fma_f32 v[10:11], v[130:131], v[46:47], v[10:11] op_sel_hi:[0,1,1]
	v_pk_fma_f32 v[12:13], v[132:133], v[46:47], v[12:13] op_sel_hi:[0,1,1]
	v_pk_fma_f32 v[14:15], v[134:135], v[46:47], v[14:15] op_sel_hi:[0,1,1]
	v_pk_fma_f32 v[16:17], v[136:137], v[46:47], v[16:17] op_sel_hi:[0,1,1]
	v_pk_fma_f32 v[18:19], v[138:139], v[46:47], v[18:19] op_sel_hi:[0,1,1]
	v_pk_fma_f32 v[20:21], v[140:141], v[46:47], v[20:21] op_sel_hi:[0,1,1]
	global_store_dword v154, v54, s[14:15] offset:-4096
	s_waitcnt lgkmcnt(6)
	v_pk_mul_f32 v[38:39], v[6:7], v[56:57] op_sel_hi:[1,0]
	v_pk_mul_f32 v[40:41], v[6:7], v[56:57] op_sel:[0,1] op_sel_hi:[1,1]
	v_pk_fma_f32 v[38:39], v[8:9], v[58:59], v[38:39] op_sel_hi:[1,0,1]
	v_pk_fma_f32 v[40:41], v[8:9], v[58:59], v[40:41] op_sel:[0,1,0] op_sel_hi:[1,1,1]
	v_pk_fma_f32 v[38:39], v[10:11], v[60:61], v[38:39] op_sel_hi:[1,0,1]
	v_pk_fma_f32 v[40:41], v[10:11], v[60:61], v[40:41] op_sel:[0,1,0] op_sel_hi:[1,1,1]
	v_pk_fma_f32 v[38:39], v[12:13], v[62:63], v[38:39] op_sel_hi:[1,0,1]
	v_pk_fma_f32 v[40:41], v[12:13], v[62:63], v[40:41] op_sel:[0,1,0] op_sel_hi:[1,1,1]
	v_pk_fma_f32 v[38:39], v[14:15], v[64:65], v[38:39] op_sel_hi:[1,0,1]
	v_pk_fma_f32 v[40:41], v[14:15], v[64:65], v[40:41] op_sel:[0,1,0] op_sel_hi:[1,1,1]
	v_pk_fma_f32 v[38:39], v[16:17], v[66:67], v[38:39] op_sel_hi:[1,0,1]
	v_pk_fma_f32 v[40:41], v[16:17], v[66:67], v[40:41] op_sel:[0,1,0] op_sel_hi:[1,1,1]
	v_pk_fma_f32 v[38:39], v[18:19], v[68:69], v[38:39] op_sel_hi:[1,0,1]
	v_pk_fma_f32 v[40:41], v[18:19], v[68:69], v[40:41] op_sel:[0,1,0] op_sel_hi:[1,1,1]
	v_pk_fma_f32 v[38:39], v[20:21], v[70:71], v[38:39] op_sel_hi:[1,0,1]
	v_pk_fma_f32 v[40:41], v[20:21], v[70:71], v[40:41] op_sel:[0,1,0] op_sel_hi:[1,1,1]
	v_mul_f32_e32 v50, v76, v51
	v_add_f32_dpp v38, v38, v38 row_ror:8 row_mask:0xf bank_mask:0x3 bound_ctrl:1
	v_add_f32_dpp v39, v39, v39 row_ror:8 row_mask:0xf bank_mask:0x3 bound_ctrl:1
	v_add_f32_dpp v38, v40, v40 row_ror:8 row_mask:0xf bank_mask:0xc bound_ctrl:1
	v_add_f32_dpp v39, v41, v41 row_ror:8 row_mask:0xf bank_mask:0xc bound_ctrl:1
	ds_read_b128 v[126:129], v2 offset:22784
	v_add_f32_dpp v38, v38, v38 row_half_mirror row_mask:0xf bank_mask:0x5 bound_ctrl:1
	v_add_f32_dpp v38, v39, v39 row_half_mirror row_mask:0xf bank_mask:0xa bound_ctrl:1
	ds_read_b128 v[130:133], v2 offset:23040
	ds_read_b128 v[134:137], v2 offset:23296
	v_add_f32_dpp v38, v38, v38 quad_perm:[1,0,3,2] row_mask:0xf bank_mask:0xf bound_ctrl:1
	ds_read_b128 v[138:141], v2 offset:23552
	ds_read_b64 v[142:143], v3 offset:30464
	v_add_f32_dpp v38, v38, v38 quad_perm:[2,3,0,1] row_mask:0xf bank_mask:0xf bound_ctrl:1
	ds_read_b128 v[144:147], v1 offset:31072
	v_cmp_gt_f32_e32 vcc, 0x2b8cbccc, v50
	v_fmac_f32_dpp v72, -v38, v50 row_newbcast:0 row_mask:0xf bank_mask:0xf bound_ctrl:1
	v_fmac_f32_dpp v73, -v38, v50 row_newbcast:4 row_mask:0xf bank_mask:0xf bound_ctrl:1
	v_pk_mul_f32 v[44:45], v[72:73], v[76:77] op_sel:[0,1] op_sel_hi:[1,1]
	v_pk_mul_f32 v[48:49], v[44:45], v[78:79] op_sel_hi:[1,0]
	v_rcp_f32_e32 v52, v50
	s_add_u32 s14, s14, 0x1000
	s_addc_u32 s15, s15, 0
	v_fmac_f32_dpp v48, v38, v50 row_newbcast:8 row_mask:0xf bank_mask:0xf bound_ctrl:1
	v_fmac_f32_dpp v49, v38, v50 row_newbcast:12 row_mask:0xf bank_mask:0xf bound_ctrl:1
	s_cbranch_vccnz .Lgd2_rare1_4
.Lgd2_back1_4:
	v_cvt_pk_bf16_f32 v54, v48, v49
	v_pk_mul_f32 v[46:47], v[44:45], v[52:53] op_sel_hi:[1,0]
	v_pk_fma_f32 v[6:7], v[56:57], v[46:47], v[6:7] op_sel_hi:[0,1,1]
	v_pk_fma_f32 v[8:9], v[58:59], v[46:47], v[8:9] op_sel_hi:[0,1,1]
	v_pk_fma_f32 v[10:11], v[60:61], v[46:47], v[10:11] op_sel_hi:[0,1,1]
	v_pk_fma_f32 v[12:13], v[62:63], v[46:47], v[12:13] op_sel_hi:[0,1,1]
	v_pk_fma_f32 v[14:15], v[64:65], v[46:47], v[14:15] op_sel_hi:[0,1,1]
	v_pk_fma_f32 v[16:17], v[66:67], v[46:47], v[16:17] op_sel_hi:[0,1,1]
	v_pk_fma_f32 v[18:19], v[68:69], v[46:47], v[18:19] op_sel_hi:[0,1,1]
	v_pk_fma_f32 v[20:21], v[70:71], v[46:47], v[20:21] op_sel_hi:[0,1,1]
	global_store_dword v154, v54, s[14:15] offset:-4096
	s_waitcnt lgkmcnt(6)
	v_pk_mul_f32 v[38:39], v[6:7], v[80:81] op_sel_hi:[1,0]
	v_pk_mul_f32 v[40:41], v[6:7], v[80:81] op_sel:[0,1] op_sel_hi:[1,1]
	v_pk_fma_f32 v[38:39], v[8:9], v[82:83], v[38:39] op_sel_hi:[1,0,1]
	v_pk_fma_f32 v[40:41], v[8:9], v[82:83], v[40:41] op_sel:[0,1,0] op_sel_hi:[1,1,1]
	v_pk_fma_f32 v[38:39], v[10:11], v[84:85], v[38:39] op_sel_hi:[1,0,1]
	v_pk_fma_f32 v[40:41], v[10:11], v[84:85], v[40:41] op_sel:[0,1,0] op_sel_hi:[1,1,1]
	v_pk_fma_f32 v[38:39], v[12:13], v[86:87], v[38:39] op_sel_hi:[1,0,1]
	v_pk_fma_f32 v[40:41], v[12:13], v[86:87], v[40:41] op_sel:[0,1,0] op_sel_hi:[1,1,1]
	v_pk_fma_f32 v[38:39], v[14:15], v[88:89], v[38:39] op_sel_hi:[1,0,1]
	v_pk_fma_f32 v[40:41], v[14:15], v[88:89], v[40:41] op_sel:[0,1,0] op_sel_hi:[1,1,1]
	v_pk_fma_f32 v[38:39], v[16:17], v[90:91], v[38:39] op_sel_hi:[1,0,1]
	v_pk_fma_f32 v[40:41], v[16:17], v[90:91], v[40:41] op_sel:[0,1,0] op_sel_hi:[1,1,1]
	v_pk_fma_f32 v[38:39], v[18:19], v[92:93], v[38:39] op_sel_hi:[1,0,1]
	v_pk_fma_f32 v[40:41], v[18:19], v[92:93], v[40:41] op_sel:[0,1,0] op_sel_hi:[1,1,1]
	v_pk_fma_f32 v[38:39], v[20:21], v[94:95], v[38:39] op_sel_hi:[1,0,1]
	v_pk_fma_f32 v[40:41], v[20:21], v[94:95], v[40:41] op_sel:[0,1,0] op_sel_hi:[1,1,1]
	v_mul_f32_e32 v51, v100, v50
	v_add_f32_dpp v38, v38, v38 row_ror:8 row_mask:0xf bank_mask:0x3 bound_ctrl:1
	v_add_f32_dpp v39, v39, v39 row_ror:8 row_mask:0xf bank_mask:0x3 bound_ctrl:1
	v_add_f32_dpp v38, v40, v40 row_ror:8 row_mask:0xf bank_mask:0xc bound_ctrl:1
	v_add_f32_dpp v39, v41, v41 row_ror:8 row_mask:0xf bank_mask:0xc bound_ctrl:1
	ds_read_b128 v[56:59], v2 offset:23808
	v_add_f32_dpp v38, v38, v38 row_half_mirror row_mask:0xf bank_mask:0x5 bound_ctrl:1
	v_add_f32_dpp v38, v39, v39 row_half_mirror row_mask:0xf bank_mask:0xa bound_ctrl:1
	ds_read_b128 v[60:63], v2 offset:24064
	ds_read_b128 v[64:67], v2 offset:24320
	v_add_f32_dpp v38, v38, v38 quad_perm:[1,0,3,2] row_mask:0xf bank_mask:0xf bound_ctrl:1
	ds_read_b128 v[68:71], v2 offset:24576
	ds_read_b64 v[72:73], v3 offset:30720
	v_add_f32_dpp v38, v38, v38 quad_perm:[2,3,0,1] row_mask:0xf bank_mask:0xf bound_ctrl:1
	ds_read_b128 v[76:79], v1 offset:31088
	v_cmp_gt_f32_e32 vcc, 0x2b8cbccc, v51
	v_fmac_f32_dpp v96, -v38, v51 row_newbcast:0 row_mask:0xf bank_mask:0xf bound_ctrl:1
	v_fmac_f32_dpp v97, -v38, v51 row_newbcast:4 row_mask:0xf bank_mask:0xf bound_ctrl:1
	v_pk_mul_f32 v[44:45], v[96:97], v[100:101] op_sel:[0,1] op_sel_hi:[1,1]
	v_pk_mul_f32 v[48:49], v[44:45], v[102:103] op_sel_hi:[1,0]
	v_rcp_f32_e32 v52, v51
	s_add_u32 s14, s14, 0x1000
	s_addc_u32 s15, s15, 0
	v_fmac_f32_dpp v48, v38, v51 row_newbcast:8 row_mask:0xf bank_mask:0xf bound_ctrl:1
	v_fmac_f32_dpp v49, v38, v51 row_newbcast:12 row_mask:0xf bank_mask:0xf bound_ctrl:1
	s_cbranch_vccnz .Lgd2_rare1_5
.Lgd2_back1_5:
	v_cvt_pk_bf16_f32 v54, v48, v49
	v_pk_mul_f32 v[46:47], v[44:45], v[52:53] op_sel_hi:[1,0]
	v_pk_fma_f32 v[6:7], v[80:81], v[46:47], v[6:7] op_sel_hi:[0,1,1]
	v_pk_fma_f32 v[8:9], v[82:83], v[46:47], v[8:9] op_sel_hi:[0,1,1]
	v_pk_fma_f32 v[10:11], v[84:85], v[46:47], v[10:11] op_sel_hi:[0,1,1]
	v_pk_fma_f32 v[12:13], v[86:87], v[46:47], v[12:13] op_sel_hi:[0,1,1]
	v_pk_fma_f32 v[14:15], v[88:89], v[46:47], v[14:15] op_sel_hi:[0,1,1]
	v_pk_fma_f32 v[16:17], v[90:91], v[46:47], v[16:17] op_sel_hi:[0,1,1]
	v_pk_fma_f32 v[18:19], v[92:93], v[46:47], v[18:19] op_sel_hi:[0,1,1]
	v_pk_fma_f32 v[20:21], v[94:95], v[46:47], v[20:21] op_sel_hi:[0,1,1]
	global_store_dword v154, v54, s[14:15] offset:-4096
	s_waitcnt lgkmcnt(6)
	v_pk_mul_f32 v[38:39], v[6:7], v[126:127] op_sel_hi:[1,0]
	v_pk_mul_f32 v[40:41], v[6:7], v[126:127] op_sel:[0,1] op_sel_hi:[1,1]
	v_pk_fma_f32 v[38:39], v[8:9], v[128:129], v[38:39] op_sel_hi:[1,0,1]
	v_pk_fma_f32 v[40:41], v[8:9], v[128:129], v[40:41] op_sel:[0,1,0] op_sel_hi:[1,1,1]
	v_pk_fma_f32 v[38:39], v[10:11], v[130:131], v[38:39] op_sel_hi:[1,0,1]
	v_pk_fma_f32 v[40:41], v[10:11], v[130:131], v[40:41] op_sel:[0,1,0] op_sel_hi:[1,1,1]
	v_pk_fma_f32 v[38:39], v[12:13], v[132:133], v[38:39] op_sel_hi:[1,0,1]
	v_pk_fma_f32 v[40:41], v[12:13], v[132:133], v[40:41] op_sel:[0,1,0] op_sel_hi:[1,1,1]
	v_pk_fma_f32 v[38:39], v[14:15], v[134:135], v[38:39] op_sel_hi:[1,0,1]
	v_pk_fma_f32 v[40:41], v[14:15], v[134:135], v[40:41] op_sel:[0,1,0] op_sel_hi:[1,1,1]
	v_pk_fma_f32 v[38:39], v[16:17], v[136:137], v[38:39] op_sel_hi:[1,0,1]
	v_pk_fma_f32 v[40:41], v[16:17], v[136:137], v[40:41] op_sel:[0,1,0] op_sel_hi:[1,1,1]
	v_pk_fma_f32 v[38:39], v[18:19], v[138:139], v[38:39] op_sel_hi:[1,0,1]
	v_pk_fma_f32 v[40:41], v[18:19], v[138:139], v[40:41] op_sel:[0,1,0] op_sel_hi:[1,1,1]
	v_pk_fma_f32 v[38:39], v[20:21], v[140:141], v[38:39] op_sel_hi:[1,0,1]
	v_pk_fma_f32 v[40:41], v[20:21], v[140:141], v[40:41] op_sel:[0,1,0] op_sel_hi:[1,1,1]
	v_mul_f32_e32 v50, v144, v51
	v_add_f32_dpp v38, v38, v38 row_ror:8 row_mask:0xf bank_mask:0x3 bound_ctrl:1
	v_add_f32_dpp v39, v39, v39 row_ror:8 row_mask:0xf bank_mask:0x3 bound_ctrl:1
	v_add_f32_dpp v38, v40, v40 row_ror:8 row_mask:0xf bank_mask:0xc bound_ctrl:1
	v_add_f32_dpp v39, v41, v41 row_ror:8 row_mask:0xf bank_mask:0xc bound_ctrl:1
	ds_read_b128 v[80:83], v2 offset:33024
	v_add_f32_dpp v38, v38, v38 row_half_mirror row_mask:0xf bank_mask:0x5 bound_ctrl:1
	v_add_f32_dpp v38, v39, v39 row_half_mirror row_mask:0xf bank_mask:0xa bound_ctrl:1
	ds_read_b128 v[84:87], v2 offset:33280
	ds_read_b128 v[88:91], v2 offset:33536
	v_add_f32_dpp v38, v38, v38 quad_perm:[1,0,3,2] row_mask:0xf bank_mask:0xf bound_ctrl:1
	ds_read_b128 v[92:95], v2 offset:33792
	ds_read_b64 v[96:97], v3 offset:45312
	v_add_f32_dpp v38, v38, v38 quad_perm:[2,3,0,1] row_mask:0xf bank_mask:0xf bound_ctrl:1
	ds_read_b128 v[100:103], v1 offset:47360
	v_cmp_gt_f32_e32 vcc, 0x2b8cbccc, v50
	v_fmac_f32_dpp v142, -v38, v50 row_newbcast:0 row_mask:0xf bank_mask:0xf bound_ctrl:1
	v_fmac_f32_dpp v143, -v38, v50 row_newbcast:4 row_mask:0xf bank_mask:0xf bound_ctrl:1
	v_pk_mul_f32 v[44:45], v[142:143], v[144:145] op_sel:[0,1] op_sel_hi:[1,1]
	v_pk_mul_f32 v[48:49], v[44:45], v[146:147] op_sel_hi:[1,0]
	v_rcp_f32_e32 v52, v50
	s_add_u32 s14, s14, 0x1000
	s_addc_u32 s15, s15, 0
	v_fmac_f32_dpp v48, v38, v50 row_newbcast:8 row_mask:0xf bank_mask:0xf bound_ctrl:1
	v_fmac_f32_dpp v49, v38, v50 row_newbcast:12 row_mask:0xf bank_mask:0xf bound_ctrl:1
	s_cbranch_vccnz .Lgd2_rare1_6
.Lgd2_back1_6:
	v_cvt_pk_bf16_f32 v54, v48, v49
	v_pk_mul_f32 v[46:47], v[44:45], v[52:53] op_sel_hi:[1,0]
	v_pk_fma_f32 v[6:7], v[126:127], v[46:47], v[6:7] op_sel_hi:[0,1,1]
	v_pk_fma_f32 v[8:9], v[128:129], v[46:47], v[8:9] op_sel_hi:[0,1,1]
	v_pk_fma_f32 v[10:11], v[130:131], v[46:47], v[10:11] op_sel_hi:[0,1,1]
	v_pk_fma_f32 v[12:13], v[132:133], v[46:47], v[12:13] op_sel_hi:[0,1,1]
	v_pk_fma_f32 v[14:15], v[134:135], v[46:47], v[14:15] op_sel_hi:[0,1,1]
	v_pk_fma_f32 v[16:17], v[136:137], v[46:47], v[16:17] op_sel_hi:[0,1,1]
	v_pk_fma_f32 v[18:19], v[138:139], v[46:47], v[18:19] op_sel_hi:[0,1,1]
	v_pk_fma_f32 v[20:21], v[140:141], v[46:47], v[20:21] op_sel_hi:[0,1,1]
	global_store_dword v154, v54, s[14:15] offset:-4096
	s_waitcnt lgkmcnt(6)
	v_pk_mul_f32 v[38:39], v[6:7], v[56:57] op_sel_hi:[1,0]
	v_pk_mul_f32 v[40:41], v[6:7], v[56:57] op_sel:[0,1] op_sel_hi:[1,1]
	v_pk_fma_f32 v[38:39], v[8:9], v[58:59], v[38:39] op_sel_hi:[1,0,1]
	v_pk_fma_f32 v[40:41], v[8:9], v[58:59], v[40:41] op_sel:[0,1,0] op_sel_hi:[1,1,1]
	v_pk_fma_f32 v[38:39], v[10:11], v[60:61], v[38:39] op_sel_hi:[1,0,1]
	v_pk_fma_f32 v[40:41], v[10:11], v[60:61], v[40:41] op_sel:[0,1,0] op_sel_hi:[1,1,1]
	v_pk_fma_f32 v[38:39], v[12:13], v[62:63], v[38:39] op_sel_hi:[1,0,1]
	v_pk_fma_f32 v[40:41], v[12:13], v[62:63], v[40:41] op_sel:[0,1,0] op_sel_hi:[1,1,1]
	v_pk_fma_f32 v[38:39], v[14:15], v[64:65], v[38:39] op_sel_hi:[1,0,1]
	v_pk_fma_f32 v[40:41], v[14:15], v[64:65], v[40:41] op_sel:[0,1,0] op_sel_hi:[1,1,1]
	v_pk_fma_f32 v[38:39], v[16:17], v[66:67], v[38:39] op_sel_hi:[1,0,1]
	v_pk_fma_f32 v[40:41], v[16:17], v[66:67], v[40:41] op_sel:[0,1,0] op_sel_hi:[1,1,1]
	v_pk_fma_f32 v[38:39], v[18:19], v[68:69], v[38:39] op_sel_hi:[1,0,1]
	v_pk_fma_f32 v[40:41], v[18:19], v[68:69], v[40:41] op_sel:[0,1,0] op_sel_hi:[1,1,1]
	v_pk_fma_f32 v[38:39], v[20:21], v[70:71], v[38:39] op_sel_hi:[1,0,1]
	v_pk_fma_f32 v[40:41], v[20:21], v[70:71], v[40:41] op_sel:[0,1,0] op_sel_hi:[1,1,1]
	v_mul_f32_e32 v51, v76, v50
	v_add_f32_dpp v38, v38, v38 row_ror:8 row_mask:0xf bank_mask:0x3 bound_ctrl:1
	v_add_f32_dpp v39, v39, v39 row_ror:8 row_mask:0xf bank_mask:0x3 bound_ctrl:1
	v_add_f32_dpp v38, v40, v40 row_ror:8 row_mask:0xf bank_mask:0xc bound_ctrl:1
	v_add_f32_dpp v39, v41, v41 row_ror:8 row_mask:0xf bank_mask:0xc bound_ctrl:1
	ds_read_b128 v[126:129], v2 offset:34048
	v_add_f32_dpp v38, v38, v38 row_half_mirror row_mask:0xf bank_mask:0x5 bound_ctrl:1
	v_add_f32_dpp v38, v39, v39 row_half_mirror row_mask:0xf bank_mask:0xa bound_ctrl:1
	ds_read_b128 v[130:133], v2 offset:34304
	ds_read_b128 v[134:137], v2 offset:34560
	v_add_f32_dpp v38, v38, v38 quad_perm:[1,0,3,2] row_mask:0xf bank_mask:0xf bound_ctrl:1
	ds_read_b128 v[138:141], v2 offset:34816
	ds_read_b64 v[142:143], v3 offset:45568
	v_add_f32_dpp v38, v38, v38 quad_perm:[2,3,0,1] row_mask:0xf bank_mask:0xf bound_ctrl:1
	ds_read_b128 v[144:147], v1 offset:47376
	v_cmp_gt_f32_e32 vcc, 0x2b8cbccc, v51
	v_fmac_f32_dpp v72, -v38, v51 row_newbcast:0 row_mask:0xf bank_mask:0xf bound_ctrl:1
	v_fmac_f32_dpp v73, -v38, v51 row_newbcast:4 row_mask:0xf bank_mask:0xf bound_ctrl:1
	v_pk_mul_f32 v[44:45], v[72:73], v[76:77] op_sel:[0,1] op_sel_hi:[1,1]
	v_pk_mul_f32 v[48:49], v[44:45], v[78:79] op_sel_hi:[1,0]
	v_rcp_f32_e32 v52, v51
	s_add_u32 s14, s14, 0x1000
	s_addc_u32 s15, s15, 0
	v_fmac_f32_dpp v48, v38, v51 row_newbcast:8 row_mask:0xf bank_mask:0xf bound_ctrl:1
	v_fmac_f32_dpp v49, v38, v51 row_newbcast:12 row_mask:0xf bank_mask:0xf bound_ctrl:1
	s_cbranch_vccnz .Lgd2_rare1_7
.Lgd2_back1_7:
	v_cvt_pk_bf16_f32 v54, v48, v49
	v_pk_mul_f32 v[46:47], v[44:45], v[52:53] op_sel_hi:[1,0]
	v_pk_fma_f32 v[6:7], v[56:57], v[46:47], v[6:7] op_sel_hi:[0,1,1]
	v_pk_fma_f32 v[8:9], v[58:59], v[46:47], v[8:9] op_sel_hi:[0,1,1]
	v_pk_fma_f32 v[10:11], v[60:61], v[46:47], v[10:11] op_sel_hi:[0,1,1]
	v_pk_fma_f32 v[12:13], v[62:63], v[46:47], v[12:13] op_sel_hi:[0,1,1]
	v_pk_fma_f32 v[14:15], v[64:65], v[46:47], v[14:15] op_sel_hi:[0,1,1]
	v_pk_fma_f32 v[16:17], v[66:67], v[46:47], v[16:17] op_sel_hi:[0,1,1]
	v_pk_fma_f32 v[18:19], v[68:69], v[46:47], v[18:19] op_sel_hi:[0,1,1]
	v_pk_fma_f32 v[20:21], v[70:71], v[46:47], v[20:21] op_sel_hi:[0,1,1]
	global_store_dword v154, v54, s[14:15] offset:-4096
	s_waitcnt vmcnt(8)
	v_lshlrev_b32_e32 v116, 16, v108
	v_lshlrev_b32_e32 v117, 16, v109
	v_and_b32_e32 v118, s17, v108
	v_and_b32_e32 v119, s17, v109
	v_lshlrev_b32_e32 v120, 16, v110
	v_and_b32_e32 v121, s17, v110
	v_lshlrev_b32_e32 v122, 16, v111
	v_and_b32_e32 v123, s17, v111
	v_lshlrev_b32_e32 v124, 16, v112
	v_and_b32_e32 v125, s17, v112
	ds_write_b128 v32, v[116:119] offset:256
	ds_write_b64 v33, v[120:121] offset:256
	ds_write_b64 v34, v[122:123] offset:256
	ds_write_b64 v34, v[124:125] offset:384
	ds_write_b32 v35, v113 offset:256
	s_add_i32 s16, s16, 8
	s_waitcnt lgkmcnt(0)
	s_barrier
	s_cmpk_lt_u32 s16, 0x800
	s_cbranch_scc0 .Lgd2_done
	global_load_dword v108, v36, s[8:9]
	global_load_dword v109, v36, s[8:9] offset:-2048
	global_load_dword v111, v104, s[8:9] offset:2048
	global_load_dword v110, v37, s[10:11]
	global_load_dword v112, v105, s[10:11]
	global_load_dword v113, v106, s[12:13]
	s_add_u32 s8, s8, 0xc000
	s_addc_u32 s9, s9, 0
	s_add_u32 s10, s10, 0x20000
	s_addc_u32 s11, s11, 0
	s_add_u32 s12, s12, 0x400
	s_addc_u32 s13, s13, 0
	s_waitcnt lgkmcnt(6)
	v_pk_mul_f32 v[38:39], v[6:7], v[80:81] op_sel_hi:[1,0]
	v_pk_mul_f32 v[40:41], v[6:7], v[80:81] op_sel:[0,1] op_sel_hi:[1,1]
	v_pk_fma_f32 v[38:39], v[8:9], v[82:83], v[38:39] op_sel_hi:[1,0,1]
	v_pk_fma_f32 v[40:41], v[8:9], v[82:83], v[40:41] op_sel:[0,1,0] op_sel_hi:[1,1,1]
	v_pk_fma_f32 v[38:39], v[10:11], v[84:85], v[38:39] op_sel_hi:[1,0,1]
	v_pk_fma_f32 v[40:41], v[10:11], v[84:85], v[40:41] op_sel:[0,1,0] op_sel_hi:[1,1,1]
	v_pk_fma_f32 v[38:39], v[12:13], v[86:87], v[38:39] op_sel_hi:[1,0,1]
	v_pk_fma_f32 v[40:41], v[12:13], v[86:87], v[40:41] op_sel:[0,1,0] op_sel_hi:[1,1,1]
	v_pk_fma_f32 v[38:39], v[14:15], v[88:89], v[38:39] op_sel_hi:[1,0,1]
	v_pk_fma_f32 v[40:41], v[14:15], v[88:89], v[40:41] op_sel:[0,1,0] op_sel_hi:[1,1,1]
	v_pk_fma_f32 v[38:39], v[16:17], v[90:91], v[38:39] op_sel_hi:[1,0,1]
	v_pk_fma_f32 v[40:41], v[16:17], v[90:91], v[40:41] op_sel:[0,1,0] op_sel_hi:[1,1,1]
	v_pk_fma_f32 v[38:39], v[18:19], v[92:93], v[38:39] op_sel_hi:[1,0,1]
	v_pk_fma_f32 v[40:41], v[18:19], v[92:93], v[40:41] op_sel:[0,1,0] op_sel_hi:[1,1,1]
	v_pk_fma_f32 v[38:39], v[20:21], v[94:95], v[38:39] op_sel_hi:[1,0,1]
	v_pk_fma_f32 v[40:41], v[20:21], v[94:95], v[40:41] op_sel:[0,1,0] op_sel_hi:[1,1,1]
	v_mul_f32_e32 v50, v100, v51
	v_add_f32_dpp v38, v38, v38 row_ror:8 row_mask:0xf bank_mask:0x3 bound_ctrl:1
	v_add_f32_dpp v39, v39, v39 row_ror:8 row_mask:0xf bank_mask:0x3 bound_ctrl:1
	v_add_f32_dpp v38, v40, v40 row_ror:8 row_mask:0xf bank_mask:0xc bound_ctrl:1
	v_add_f32_dpp v39, v41, v41 row_ror:8 row_mask:0xf bank_mask:0xc bound_ctrl:1
	ds_read_b128 v[56:59], v2 offset:35072
	v_add_f32_dpp v38, v38, v38 row_half_mirror row_mask:0xf bank_mask:0x5 bound_ctrl:1
	v_add_f32_dpp v38, v39, v39 row_half_mirror row_mask:0xf bank_mask:0xa bound_ctrl:1
	ds_read_b128 v[60:63], v2 offset:35328
	ds_read_b128 v[64:67], v2 offset:35584
	v_add_f32_dpp v38, v38, v38 quad_perm:[1,0,3,2] row_mask:0xf bank_mask:0xf bound_ctrl:1
	ds_read_b128 v[68:71], v2 offset:35840
	ds_read_b64 v[72:73], v3 offset:45824
	v_add_f32_dpp v38, v38, v38 quad_perm:[2,3,0,1] row_mask:0xf bank_mask:0xf bound_ctrl:1
	ds_read_b128 v[76:79], v1 offset:47392
	v_cmp_gt_f32_e32 vcc, 0x2b8cbccc, v50
	v_fmac_f32_dpp v96, -v38, v50 row_newbcast:0 row_mask:0xf bank_mask:0xf bound_ctrl:1
	v_fmac_f32_dpp v97, -v38, v50 row_newbcast:4 row_mask:0xf bank_mask:0xf bound_ctrl:1
	v_pk_mul_f32 v[44:45], v[96:97], v[100:101] op_sel:[0,1] op_sel_hi:[1,1]
	v_pk_mul_f32 v[48:49], v[44:45], v[102:103] op_sel_hi:[1,0]
	v_rcp_f32_e32 v52, v50
	s_add_u32 s14, s14, 0x1000
	s_addc_u32 s15, s15, 0
	v_fmac_f32_dpp v48, v38, v50 row_newbcast:8 row_mask:0xf bank_mask:0xf bound_ctrl:1
	v_fmac_f32_dpp v49, v38, v50 row_newbcast:12 row_mask:0xf bank_mask:0xf bound_ctrl:1
	s_cbranch_vccnz .Lgd2_rare2_0
.Lgd2_back2_0:
	v_cvt_pk_bf16_f32 v54, v48, v49
	v_pk_mul_f32 v[46:47], v[44:45], v[52:53] op_sel_hi:[1,0]
	v_pk_fma_f32 v[6:7], v[80:81], v[46:47], v[6:7] op_sel_hi:[0,1,1]
	v_pk_fma_f32 v[8:9], v[82:83], v[46:47], v[8:9] op_sel_hi:[0,1,1]
	v_pk_fma_f32 v[10:11], v[84:85], v[46:47], v[10:11] op_sel_hi:[0,1,1]
	v_pk_fma_f32 v[12:13], v[86:87], v[46:47], v[12:13] op_sel_hi:[0,1,1]
	v_pk_fma_f32 v[14:15], v[88:89], v[46:47], v[14:15] op_sel_hi:[0,1,1]
	v_pk_fma_f32 v[16:17], v[90:91], v[46:47], v[16:17] op_sel_hi:[0,1,1]
	v_pk_fma_f32 v[18:19], v[92:93], v[46:47], v[18:19] op_sel_hi:[0,1,1]
	v_pk_fma_f32 v[20:21], v[94:95], v[46:47], v[20:21] op_sel_hi:[0,1,1]
	global_store_dword v154, v54, s[14:15] offset:-4096
	s_waitcnt lgkmcnt(6)
	v_pk_mul_f32 v[38:39], v[6:7], v[126:127] op_sel_hi:[1,0]
	v_pk_mul_f32 v[40:41], v[6:7], v[126:127] op_sel:[0,1] op_sel_hi:[1,1]
	v_pk_fma_f32 v[38:39], v[8:9], v[128:129], v[38:39] op_sel_hi:[1,0,1]
	v_pk_fma_f32 v[40:41], v[8:9], v[128:129], v[40:41] op_sel:[0,1,0] op_sel_hi:[1,1,1]
	v_pk_fma_f32 v[38:39], v[10:11], v[130:131], v[38:39] op_sel_hi:[1,0,1]
	v_pk_fma_f32 v[40:41], v[10:11], v[130:131], v[40:41] op_sel:[0,1,0] op_sel_hi:[1,1,1]
	v_pk_fma_f32 v[38:39], v[12:13], v[132:133], v[38:39] op_sel_hi:[1,0,1]
	v_pk_fma_f32 v[40:41], v[12:13], v[132:133], v[40:41] op_sel:[0,1,0] op_sel_hi:[1,1,1]
	v_pk_fma_f32 v[38:39], v[14:15], v[134:135], v[38:39] op_sel_hi:[1,0,1]
	v_pk_fma_f32 v[40:41], v[14:15], v[134:135], v[40:41] op_sel:[0,1,0] op_sel_hi:[1,1,1]
	v_pk_fma_f32 v[38:39], v[16:17], v[136:137], v[38:39] op_sel_hi:[1,0,1]
	v_pk_fma_f32 v[40:41], v[16:17], v[136:137], v[40:41] op_sel:[0,1,0] op_sel_hi:[1,1,1]
	v_pk_fma_f32 v[38:39], v[18:19], v[138:139], v[38:39] op_sel_hi:[1,0,1]
	v_pk_fma_f32 v[40:41], v[18:19], v[138:139], v[40:41] op_sel:[0,1,0] op_sel_hi:[1,1,1]
	v_pk_fma_f32 v[38:39], v[20:21], v[140:141], v[38:39] op_sel_hi:[1,0,1]
	v_pk_fma_f32 v[40:41], v[20:21], v[140:141], v[40:41] op_sel:[0,1,0] op_sel_hi:[1,1,1]
	v_mul_f32_e32 v51, v144, v50
	v_add_f32_dpp v38, v38, v38 row_ror:8 row_mask:0xf bank_mask:0x3 bound_ctrl:1
	v_add_f32_dpp v39, v39, v39 row_ror:8 row_mask:0xf bank_mask:0x3 bound_ctrl:1
	v_add_f32_dpp v38, v40, v40 row_ror:8 row_mask:0xf bank_mask:0xc bound_ctrl:1
	v_add_f32_dpp v39, v41, v41 row_ror:8 row_mask:0xf bank_mask:0xc bound_ctrl:1
	ds_read_b128 v[80:83], v2 offset:36096
	v_add_f32_dpp v38, v38, v38 row_half_mirror row_mask:0xf bank_mask:0x5 bound_ctrl:1
	v_add_f32_dpp v38, v39, v39 row_half_mirror row_mask:0xf bank_mask:0xa bound_ctrl:1
	ds_read_b128 v[84:87], v2 offset:36352
	ds_read_b128 v[88:91], v2 offset:36608
	v_add_f32_dpp v38, v38, v38 quad_perm:[1,0,3,2] row_mask:0xf bank_mask:0xf bound_ctrl:1
	ds_read_b128 v[92:95], v2 offset:36864
	ds_read_b64 v[96:97], v3 offset:46080
	v_add_f32_dpp v38, v38, v38 quad_perm:[2,3,0,1] row_mask:0xf bank_mask:0xf bound_ctrl:1
	ds_read_b128 v[100:103], v1 offset:47408
	v_cmp_gt_f32_e32 vcc, 0x2b8cbccc, v51
	v_fmac_f32_dpp v142, -v38, v51 row_newbcast:0 row_mask:0xf bank_mask:0xf bound_ctrl:1
	v_fmac_f32_dpp v143, -v38, v51 row_newbcast:4 row_mask:0xf bank_mask:0xf bound_ctrl:1
	v_pk_mul_f32 v[44:45], v[142:143], v[144:145] op_sel:[0,1] op_sel_hi:[1,1]
	v_pk_mul_f32 v[48:49], v[44:45], v[146:147] op_sel_hi:[1,0]
	v_rcp_f32_e32 v52, v51
	s_add_u32 s14, s14, 0x1000
	s_addc_u32 s15, s15, 0
	v_fmac_f32_dpp v48, v38, v51 row_newbcast:8 row_mask:0xf bank_mask:0xf bound_ctrl:1
	v_fmac_f32_dpp v49, v38, v51 row_newbcast:12 row_mask:0xf bank_mask:0xf bound_ctrl:1
	s_cbranch_vccnz .Lgd2_rare2_1
.Lgd2_back2_1:
	v_cvt_pk_bf16_f32 v54, v48, v49
	v_pk_mul_f32 v[46:47], v[44:45], v[52:53] op_sel_hi:[1,0]
	v_pk_fma_f32 v[6:7], v[126:127], v[46:47], v[6:7] op_sel_hi:[0,1,1]
	v_pk_fma_f32 v[8:9], v[128:129], v[46:47], v[8:9] op_sel_hi:[0,1,1]
	v_pk_fma_f32 v[10:11], v[130:131], v[46:47], v[10:11] op_sel_hi:[0,1,1]
	v_pk_fma_f32 v[12:13], v[132:133], v[46:47], v[12:13] op_sel_hi:[0,1,1]
	v_pk_fma_f32 v[14:15], v[134:135], v[46:47], v[14:15] op_sel_hi:[0,1,1]
	v_pk_fma_f32 v[16:17], v[136:137], v[46:47], v[16:17] op_sel_hi:[0,1,1]
	v_pk_fma_f32 v[18:19], v[138:139], v[46:47], v[18:19] op_sel_hi:[0,1,1]
	v_pk_fma_f32 v[20:21], v[140:141], v[46:47], v[20:21] op_sel_hi:[0,1,1]
	global_store_dword v154, v54, s[14:15] offset:-4096
	s_waitcnt lgkmcnt(6)
	v_pk_mul_f32 v[38:39], v[6:7], v[56:57] op_sel_hi:[1,0]
	v_pk_mul_f32 v[40:41], v[6:7], v[56:57] op_sel:[0,1] op_sel_hi:[1,1]
	v_pk_fma_f32 v[38:39], v[8:9], v[58:59], v[38:39] op_sel_hi:[1,0,1]
	v_pk_fma_f32 v[40:41], v[8:9], v[58:59], v[40:41] op_sel:[0,1,0] op_sel_hi:[1,1,1]
	v_pk_fma_f32 v[38:39], v[10:11], v[60:61], v[38:39] op_sel_hi:[1,0,1]
	v_pk_fma_f32 v[40:41], v[10:11], v[60:61], v[40:41] op_sel:[0,1,0] op_sel_hi:[1,1,1]
	v_pk_fma_f32 v[38:39], v[12:13], v[62:63], v[38:39] op_sel_hi:[1,0,1]
	v_pk_fma_f32 v[40:41], v[12:13], v[62:63], v[40:41] op_sel:[0,1,0] op_sel_hi:[1,1,1]
	v_pk_fma_f32 v[38:39], v[14:15], v[64:65], v[38:39] op_sel_hi:[1,0,1]
	v_pk_fma_f32 v[40:41], v[14:15], v[64:65], v[40:41] op_sel:[0,1,0] op_sel_hi:[1,1,1]
	v_pk_fma_f32 v[38:39], v[16:17], v[66:67], v[38:39] op_sel_hi:[1,0,1]
	v_pk_fma_f32 v[40:41], v[16:17], v[66:67], v[40:41] op_sel:[0,1,0] op_sel_hi:[1,1,1]
	v_pk_fma_f32 v[38:39], v[18:19], v[68:69], v[38:39] op_sel_hi:[1,0,1]
	v_pk_fma_f32 v[40:41], v[18:19], v[68:69], v[40:41] op_sel:[0,1,0] op_sel_hi:[1,1,1]
	v_pk_fma_f32 v[38:39], v[20:21], v[70:71], v[38:39] op_sel_hi:[1,0,1]
	v_pk_fma_f32 v[40:41], v[20:21], v[70:71], v[40:41] op_sel:[0,1,0] op_sel_hi:[1,1,1]
	v_mul_f32_e32 v50, v76, v51
	v_add_f32_dpp v38, v38, v38 row_ror:8 row_mask:0xf bank_mask:0x3 bound_ctrl:1
	v_add_f32_dpp v39, v39, v39 row_ror:8 row_mask:0xf bank_mask:0x3 bound_ctrl:1
	v_add_f32_dpp v38, v40, v40 row_ror:8 row_mask:0xf bank_mask:0xc bound_ctrl:1
	v_add_f32_dpp v39, v41, v41 row_ror:8 row_mask:0xf bank_mask:0xc bound_ctrl:1
	ds_read_b128 v[126:129], v2 offset:37120
	v_add_f32_dpp v38, v38, v38 row_half_mirror row_mask:0xf bank_mask:0x5 bound_ctrl:1
	v_add_f32_dpp v38, v39, v39 row_half_mirror row_mask:0xf bank_mask:0xa bound_ctrl:1
	ds_read_b128 v[130:133], v2 offset:37376
	ds_read_b128 v[134:137], v2 offset:37632
	v_add_f32_dpp v38, v38, v38 quad_perm:[1,0,3,2] row_mask:0xf bank_mask:0xf bound_ctrl:1
	ds_read_b128 v[138:141], v2 offset:37888
	ds_read_b64 v[142:143], v3 offset:46336
	v_add_f32_dpp v38, v38, v38 quad_perm:[2,3,0,1] row_mask:0xf bank_mask:0xf bound_ctrl:1
	ds_read_b128 v[144:147], v1 offset:47424
	v_cmp_gt_f32_e32 vcc, 0x2b8cbccc, v50
	v_fmac_f32_dpp v72, -v38, v50 row_newbcast:0 row_mask:0xf bank_mask:0xf bound_ctrl:1
	v_fmac_f32_dpp v73, -v38, v50 row_newbcast:4 row_mask:0xf bank_mask:0xf bound_ctrl:1
	v_pk_mul_f32 v[44:45], v[72:73], v[76:77] op_sel:[0,1] op_sel_hi:[1,1]
	v_pk_mul_f32 v[48:49], v[44:45], v[78:79] op_sel_hi:[1,0]
	v_rcp_f32_e32 v52, v50
	s_add_u32 s14, s14, 0x1000
	s_addc_u32 s15, s15, 0
	v_fmac_f32_dpp v48, v38, v50 row_newbcast:8 row_mask:0xf bank_mask:0xf bound_ctrl:1
	v_fmac_f32_dpp v49, v38, v50 row_newbcast:12 row_mask:0xf bank_mask:0xf bound_ctrl:1
	s_cbranch_vccnz .Lgd2_rare2_2
.Lgd2_back2_2:
	v_cvt_pk_bf16_f32 v54, v48, v49
	v_pk_mul_f32 v[46:47], v[44:45], v[52:53] op_sel_hi:[1,0]
	v_pk_fma_f32 v[6:7], v[56:57], v[46:47], v[6:7] op_sel_hi:[0,1,1]
	v_pk_fma_f32 v[8:9], v[58:59], v[46:47], v[8:9] op_sel_hi:[0,1,1]
	v_pk_fma_f32 v[10:11], v[60:61], v[46:47], v[10:11] op_sel_hi:[0,1,1]
	v_pk_fma_f32 v[12:13], v[62:63], v[46:47], v[12:13] op_sel_hi:[0,1,1]
	v_pk_fma_f32 v[14:15], v[64:65], v[46:47], v[14:15] op_sel_hi:[0,1,1]
	v_pk_fma_f32 v[16:17], v[66:67], v[46:47], v[16:17] op_sel_hi:[0,1,1]
	v_pk_fma_f32 v[18:19], v[68:69], v[46:47], v[18:19] op_sel_hi:[0,1,1]
	v_pk_fma_f32 v[20:21], v[70:71], v[46:47], v[20:21] op_sel_hi:[0,1,1]
	global_store_dword v154, v54, s[14:15] offset:-4096
	s_waitcnt lgkmcnt(6)
	v_pk_mul_f32 v[38:39], v[6:7], v[80:81] op_sel_hi:[1,0]
	v_pk_mul_f32 v[40:41], v[6:7], v[80:81] op_sel:[0,1] op_sel_hi:[1,1]
	v_pk_fma_f32 v[38:39], v[8:9], v[82:83], v[38:39] op_sel_hi:[1,0,1]
	v_pk_fma_f32 v[40:41], v[8:9], v[82:83], v[40:41] op_sel:[0,1,0] op_sel_hi:[1,1,1]
	v_pk_fma_f32 v[38:39], v[10:11], v[84:85], v[38:39] op_sel_hi:[1,0,1]
	v_pk_fma_f32 v[40:41], v[10:11], v[84:85], v[40:41] op_sel:[0,1,0] op_sel_hi:[1,1,1]
	v_pk_fma_f32 v[38:39], v[12:13], v[86:87], v[38:39] op_sel_hi:[1,0,1]
	v_pk_fma_f32 v[40:41], v[12:13], v[86:87], v[40:41] op_sel:[0,1,0] op_sel_hi:[1,1,1]
	v_pk_fma_f32 v[38:39], v[14:15], v[88:89], v[38:39] op_sel_hi:[1,0,1]
	v_pk_fma_f32 v[40:41], v[14:15], v[88:89], v[40:41] op_sel:[0,1,0] op_sel_hi:[1,1,1]
	v_pk_fma_f32 v[38:39], v[16:17], v[90:91], v[38:39] op_sel_hi:[1,0,1]
	v_pk_fma_f32 v[40:41], v[16:17], v[90:91], v[40:41] op_sel:[0,1,0] op_sel_hi:[1,1,1]
	v_pk_fma_f32 v[38:39], v[18:19], v[92:93], v[38:39] op_sel_hi:[1,0,1]
	v_pk_fma_f32 v[40:41], v[18:19], v[92:93], v[40:41] op_sel:[0,1,0] op_sel_hi:[1,1,1]
	v_pk_fma_f32 v[38:39], v[20:21], v[94:95], v[38:39] op_sel_hi:[1,0,1]
	v_pk_fma_f32 v[40:41], v[20:21], v[94:95], v[40:41] op_sel:[0,1,0] op_sel_hi:[1,1,1]
	v_mul_f32_e32 v51, v100, v50
	v_add_f32_dpp v38, v38, v38 row_ror:8 row_mask:0xf bank_mask:0x3 bound_ctrl:1
	v_add_f32_dpp v39, v39, v39 row_ror:8 row_mask:0xf bank_mask:0x3 bound_ctrl:1
	v_add_f32_dpp v38, v40, v40 row_ror:8 row_mask:0xf bank_mask:0xc bound_ctrl:1
	v_add_f32_dpp v39, v41, v41 row_ror:8 row_mask:0xf bank_mask:0xc bound_ctrl:1
	ds_read_b128 v[56:59], v2 offset:38144
	v_add_f32_dpp v38, v38, v38 row_half_mirror row_mask:0xf bank_mask:0x5 bound_ctrl:1
	v_add_f32_dpp v38, v39, v39 row_half_mirror row_mask:0xf bank_mask:0xa bound_ctrl:1
	ds_read_b128 v[60:63], v2 offset:38400
	ds_read_b128 v[64:67], v2 offset:38656
	v_add_f32_dpp v38, v38, v38 quad_perm:[1,0,3,2] row_mask:0xf bank_mask:0xf bound_ctrl:1
	ds_read_b128 v[68:71], v2 offset:38912
	ds_read_b64 v[72:73], v3 offset:46592
	v_add_f32_dpp v38, v38, v38 quad_perm:[2,3,0,1] row_mask:0xf bank_mask:0xf bound_ctrl:1
	ds_read_b128 v[76:79], v1 offset:47440
	v_cmp_gt_f32_e32 vcc, 0x2b8cbccc, v51
	v_fmac_f32_dpp v96, -v38, v51 row_newbcast:0 row_mask:0xf bank_mask:0xf bound_ctrl:1
	v_fmac_f32_dpp v97, -v38, v51 row_newbcast:4 row_mask:0xf bank_mask:0xf bound_ctrl:1
	v_pk_mul_f32 v[44:45], v[96:97], v[100:101] op_sel:[0,1] op_sel_hi:[1,1]
	v_pk_mul_f32 v[48:49], v[44:45], v[102:103] op_sel_hi:[1,0]
	v_rcp_f32_e32 v52, v51
	s_add_u32 s14, s14, 0x1000
	s_addc_u32 s15, s15, 0
	v_fmac_f32_dpp v48, v38, v51 row_newbcast:8 row_mask:0xf bank_mask:0xf bound_ctrl:1
	v_fmac_f32_dpp v49, v38, v51 row_newbcast:12 row_mask:0xf bank_mask:0xf bound_ctrl:1
	s_cbranch_vccnz .Lgd2_rare2_3
.Lgd2_back2_3:
	v_cvt_pk_bf16_f32 v54, v48, v49
	v_pk_mul_f32 v[46:47], v[44:45], v[52:53] op_sel_hi:[1,0]
	v_pk_fma_f32 v[6:7], v[80:81], v[46:47], v[6:7] op_sel_hi:[0,1,1]
	v_pk_fma_f32 v[8:9], v[82:83], v[46:47], v[8:9] op_sel_hi:[0,1,1]
	v_pk_fma_f32 v[10:11], v[84:85], v[46:47], v[10:11] op_sel_hi:[0,1,1]
	v_pk_fma_f32 v[12:13], v[86:87], v[46:47], v[12:13] op_sel_hi:[0,1,1]
	v_pk_fma_f32 v[14:15], v[88:89], v[46:47], v[14:15] op_sel_hi:[0,1,1]
	v_pk_fma_f32 v[16:17], v[90:91], v[46:47], v[16:17] op_sel_hi:[0,1,1]
	v_pk_fma_f32 v[18:19], v[92:93], v[46:47], v[18:19] op_sel_hi:[0,1,1]
	v_pk_fma_f32 v[20:21], v[94:95], v[46:47], v[20:21] op_sel_hi:[0,1,1]
	global_store_dword v154, v54, s[14:15] offset:-4096
	s_waitcnt lgkmcnt(6)
	v_pk_mul_f32 v[38:39], v[6:7], v[126:127] op_sel_hi:[1,0]
	v_pk_mul_f32 v[40:41], v[6:7], v[126:127] op_sel:[0,1] op_sel_hi:[1,1]
	v_pk_fma_f32 v[38:39], v[8:9], v[128:129], v[38:39] op_sel_hi:[1,0,1]
	v_pk_fma_f32 v[40:41], v[8:9], v[128:129], v[40:41] op_sel:[0,1,0] op_sel_hi:[1,1,1]
	v_pk_fma_f32 v[38:39], v[10:11], v[130:131], v[38:39] op_sel_hi:[1,0,1]
	v_pk_fma_f32 v[40:41], v[10:11], v[130:131], v[40:41] op_sel:[0,1,0] op_sel_hi:[1,1,1]
	v_pk_fma_f32 v[38:39], v[12:13], v[132:133], v[38:39] op_sel_hi:[1,0,1]
	v_pk_fma_f32 v[40:41], v[12:13], v[132:133], v[40:41] op_sel:[0,1,0] op_sel_hi:[1,1,1]
	v_pk_fma_f32 v[38:39], v[14:15], v[134:135], v[38:39] op_sel_hi:[1,0,1]
	v_pk_fma_f32 v[40:41], v[14:15], v[134:135], v[40:41] op_sel:[0,1,0] op_sel_hi:[1,1,1]
	v_pk_fma_f32 v[38:39], v[16:17], v[136:137], v[38:39] op_sel_hi:[1,0,1]
	v_pk_fma_f32 v[40:41], v[16:17], v[136:137], v[40:41] op_sel:[0,1,0] op_sel_hi:[1,1,1]
	v_pk_fma_f32 v[38:39], v[18:19], v[138:139], v[38:39] op_sel_hi:[1,0,1]
	v_pk_fma_f32 v[40:41], v[18:19], v[138:139], v[40:41] op_sel:[0,1,0] op_sel_hi:[1,1,1]
	v_pk_fma_f32 v[38:39], v[20:21], v[140:141], v[38:39] op_sel_hi:[1,0,1]
	v_pk_fma_f32 v[40:41], v[20:21], v[140:141], v[40:41] op_sel:[0,1,0] op_sel_hi:[1,1,1]
	v_mul_f32_e32 v50, v144, v51
	v_add_f32_dpp v38, v38, v38 row_ror:8 row_mask:0xf bank_mask:0x3 bound_ctrl:1
	v_add_f32_dpp v39, v39, v39 row_ror:8 row_mask:0xf bank_mask:0x3 bound_ctrl:1
	v_add_f32_dpp v38, v40, v40 row_ror:8 row_mask:0xf bank_mask:0xc bound_ctrl:1
	v_add_f32_dpp v39, v41, v41 row_ror:8 row_mask:0xf bank_mask:0xc bound_ctrl:1
	ds_read_b128 v[80:83], v2 offset:39168
	v_add_f32_dpp v38, v38, v38 row_half_mirror row_mask:0xf bank_mask:0x5 bound_ctrl:1
	v_add_f32_dpp v38, v39, v39 row_half_mirror row_mask:0xf bank_mask:0xa bound_ctrl:1
	ds_read_b128 v[84:87], v2 offset:39424
	ds_read_b128 v[88:91], v2 offset:39680
	v_add_f32_dpp v38, v38, v38 quad_perm:[1,0,3,2] row_mask:0xf bank_mask:0xf bound_ctrl:1
	ds_read_b128 v[92:95], v2 offset:39936
	ds_read_b64 v[96:97], v3 offset:46848
	v_add_f32_dpp v38, v38, v38 quad_perm:[2,3,0,1] row_mask:0xf bank_mask:0xf bound_ctrl:1
	ds_read_b128 v[100:103], v1 offset:47456
	v_cmp_gt_f32_e32 vcc, 0x2b8cbccc, v50
	v_fmac_f32_dpp v142, -v38, v50 row_newbcast:0 row_mask:0xf bank_mask:0xf bound_ctrl:1
	v_fmac_f32_dpp v143, -v38, v50 row_newbcast:4 row_mask:0xf bank_mask:0xf bound_ctrl:1
	v_pk_mul_f32 v[44:45], v[142:143], v[144:145] op_sel:[0,1] op_sel_hi:[1,1]
	v_pk_mul_f32 v[48:49], v[44:45], v[146:147] op_sel_hi:[1,0]
	v_rcp_f32_e32 v52, v50
	s_add_u32 s14, s14, 0x1000
	s_addc_u32 s15, s15, 0
	v_fmac_f32_dpp v48, v38, v50 row_newbcast:8 row_mask:0xf bank_mask:0xf bound_ctrl:1
	v_fmac_f32_dpp v49, v38, v50 row_newbcast:12 row_mask:0xf bank_mask:0xf bound_ctrl:1
	s_cbranch_vccnz .Lgd2_rare2_4
.Lgd2_back2_4:
	v_cvt_pk_bf16_f32 v54, v48, v49
	v_pk_mul_f32 v[46:47], v[44:45], v[52:53] op_sel_hi:[1,0]
	v_pk_fma_f32 v[6:7], v[126:127], v[46:47], v[6:7] op_sel_hi:[0,1,1]
	v_pk_fma_f32 v[8:9], v[128:129], v[46:47], v[8:9] op_sel_hi:[0,1,1]
	v_pk_fma_f32 v[10:11], v[130:131], v[46:47], v[10:11] op_sel_hi:[0,1,1]
	v_pk_fma_f32 v[12:13], v[132:133], v[46:47], v[12:13] op_sel_hi:[0,1,1]
	v_pk_fma_f32 v[14:15], v[134:135], v[46:47], v[14:15] op_sel_hi:[0,1,1]
	v_pk_fma_f32 v[16:17], v[136:137], v[46:47], v[16:17] op_sel_hi:[0,1,1]
	v_pk_fma_f32 v[18:19], v[138:139], v[46:47], v[18:19] op_sel_hi:[0,1,1]
	v_pk_fma_f32 v[20:21], v[140:141], v[46:47], v[20:21] op_sel_hi:[0,1,1]
	global_store_dword v154, v54, s[14:15] offset:-4096
	s_waitcnt lgkmcnt(6)
	v_pk_mul_f32 v[38:39], v[6:7], v[56:57] op_sel_hi:[1,0]
	v_pk_mul_f32 v[40:41], v[6:7], v[56:57] op_sel:[0,1] op_sel_hi:[1,1]
	v_pk_fma_f32 v[38:39], v[8:9], v[58:59], v[38:39] op_sel_hi:[1,0,1]
	v_pk_fma_f32 v[40:41], v[8:9], v[58:59], v[40:41] op_sel:[0,1,0] op_sel_hi:[1,1,1]
	v_pk_fma_f32 v[38:39], v[10:11], v[60:61], v[38:39] op_sel_hi:[1,0,1]
	v_pk_fma_f32 v[40:41], v[10:11], v[60:61], v[40:41] op_sel:[0,1,0] op_sel_hi:[1,1,1]
	v_pk_fma_f32 v[38:39], v[12:13], v[62:63], v[38:39] op_sel_hi:[1,0,1]
	v_pk_fma_f32 v[40:41], v[12:13], v[62:63], v[40:41] op_sel:[0,1,0] op_sel_hi:[1,1,1]
	v_pk_fma_f32 v[38:39], v[14:15], v[64:65], v[38:39] op_sel_hi:[1,0,1]
	v_pk_fma_f32 v[40:41], v[14:15], v[64:65], v[40:41] op_sel:[0,1,0] op_sel_hi:[1,1,1]
	v_pk_fma_f32 v[38:39], v[16:17], v[66:67], v[38:39] op_sel_hi:[1,0,1]
	v_pk_fma_f32 v[40:41], v[16:17], v[66:67], v[40:41] op_sel:[0,1,0] op_sel_hi:[1,1,1]
	v_pk_fma_f32 v[38:39], v[18:19], v[68:69], v[38:39] op_sel_hi:[1,0,1]
	v_pk_fma_f32 v[40:41], v[18:19], v[68:69], v[40:41] op_sel:[0,1,0] op_sel_hi:[1,1,1]
	v_pk_fma_f32 v[38:39], v[20:21], v[70:71], v[38:39] op_sel_hi:[1,0,1]
	v_pk_fma_f32 v[40:41], v[20:21], v[70:71], v[40:41] op_sel:[0,1,0] op_sel_hi:[1,1,1]
	v_mul_f32_e32 v51, v76, v50
	v_add_f32_dpp v38, v38, v38 row_ror:8 row_mask:0xf bank_mask:0x3 bound_ctrl:1
	v_add_f32_dpp v39, v39, v39 row_ror:8 row_mask:0xf bank_mask:0x3 bound_ctrl:1
	v_add_f32_dpp v38, v40, v40 row_ror:8 row_mask:0xf bank_mask:0xc bound_ctrl:1
	v_add_f32_dpp v39, v41, v41 row_ror:8 row_mask:0xf bank_mask:0xc bound_ctrl:1
	ds_read_b128 v[126:129], v2 offset:40192
	v_add_f32_dpp v38, v38, v38 row_half_mirror row_mask:0xf bank_mask:0x5 bound_ctrl:1
	v_add_f32_dpp v38, v39, v39 row_half_mirror row_mask:0xf bank_mask:0xa bound_ctrl:1
	ds_read_b128 v[130:133], v2 offset:40448
	ds_read_b128 v[134:137], v2 offset:40704
	v_add_f32_dpp v38, v38, v38 quad_perm:[1,0,3,2] row_mask:0xf bank_mask:0xf bound_ctrl:1
	ds_read_b128 v[138:141], v2 offset:40960
	ds_read_b64 v[142:143], v3 offset:47104
	v_add_f32_dpp v38, v38, v38 quad_perm:[2,3,0,1] row_mask:0xf bank_mask:0xf bound_ctrl:1
	ds_read_b128 v[144:147], v1 offset:47472
	v_cmp_gt_f32_e32 vcc, 0x2b8cbccc, v51
	v_fmac_f32_dpp v72, -v38, v51 row_newbcast:0 row_mask:0xf bank_mask:0xf bound_ctrl:1
	v_fmac_f32_dpp v73, -v38, v51 row_newbcast:4 row_mask:0xf bank_mask:0xf bound_ctrl:1
	v_pk_mul_f32 v[44:45], v[72:73], v[76:77] op_sel:[0,1] op_sel_hi:[1,1]
	v_pk_mul_f32 v[48:49], v[44:45], v[78:79] op_sel_hi:[1,0]
	v_rcp_f32_e32 v52, v51
	s_add_u32 s14, s14, 0x1000
	s_addc_u32 s15, s15, 0
	v_fmac_f32_dpp v48, v38, v51 row_newbcast:8 row_mask:0xf bank_mask:0xf bound_ctrl:1
	v_fmac_f32_dpp v49, v38, v51 row_newbcast:12 row_mask:0xf bank_mask:0xf bound_ctrl:1
	s_cbranch_vccnz .Lgd2_rare2_5
.Lgd2_back2_5:
	v_cvt_pk_bf16_f32 v54, v48, v49
	v_pk_mul_f32 v[46:47], v[44:45], v[52:53] op_sel_hi:[1,0]
	v_pk_fma_f32 v[6:7], v[56:57], v[46:47], v[6:7] op_sel_hi:[0,1,1]
	v_pk_fma_f32 v[8:9], v[58:59], v[46:47], v[8:9] op_sel_hi:[0,1,1]
	v_pk_fma_f32 v[10:11], v[60:61], v[46:47], v[10:11] op_sel_hi:[0,1,1]
	v_pk_fma_f32 v[12:13], v[62:63], v[46:47], v[12:13] op_sel_hi:[0,1,1]
	v_pk_fma_f32 v[14:15], v[64:65], v[46:47], v[14:15] op_sel_hi:[0,1,1]
	v_pk_fma_f32 v[16:17], v[66:67], v[46:47], v[16:17] op_sel_hi:[0,1,1]
	v_pk_fma_f32 v[18:19], v[68:69], v[46:47], v[18:19] op_sel_hi:[0,1,1]
	v_pk_fma_f32 v[20:21], v[70:71], v[46:47], v[20:21] op_sel_hi:[0,1,1]
	global_store_dword v154, v54, s[14:15] offset:-4096
	s_waitcnt lgkmcnt(6)
	v_pk_mul_f32 v[38:39], v[6:7], v[80:81] op_sel_hi:[1,0]
	v_pk_mul_f32 v[40:41], v[6:7], v[80:81] op_sel:[0,1] op_sel_hi:[1,1]
	v_pk_fma_f32 v[38:39], v[8:9], v[82:83], v[38:39] op_sel_hi:[1,0,1]
	v_pk_fma_f32 v[40:41], v[8:9], v[82:83], v[40:41] op_sel:[0,1,0] op_sel_hi:[1,1,1]
	v_pk_fma_f32 v[38:39], v[10:11], v[84:85], v[38:39] op_sel_hi:[1,0,1]
	v_pk_fma_f32 v[40:41], v[10:11], v[84:85], v[40:41] op_sel:[0,1,0] op_sel_hi:[1,1,1]
	v_pk_fma_f32 v[38:39], v[12:13], v[86:87], v[38:39] op_sel_hi:[1,0,1]
	v_pk_fma_f32 v[40:41], v[12:13], v[86:87], v[40:41] op_sel:[0,1,0] op_sel_hi:[1,1,1]
	v_pk_fma_f32 v[38:39], v[14:15], v[88:89], v[38:39] op_sel_hi:[1,0,1]
	v_pk_fma_f32 v[40:41], v[14:15], v[88:89], v[40:41] op_sel:[0,1,0] op_sel_hi:[1,1,1]
	v_pk_fma_f32 v[38:39], v[16:17], v[90:91], v[38:39] op_sel_hi:[1,0,1]
	v_pk_fma_f32 v[40:41], v[16:17], v[90:91], v[40:41] op_sel:[0,1,0] op_sel_hi:[1,1,1]
	v_pk_fma_f32 v[38:39], v[18:19], v[92:93], v[38:39] op_sel_hi:[1,0,1]
	v_pk_fma_f32 v[40:41], v[18:19], v[92:93], v[40:41] op_sel:[0,1,0] op_sel_hi:[1,1,1]
	v_pk_fma_f32 v[38:39], v[20:21], v[94:95], v[38:39] op_sel_hi:[1,0,1]
	v_pk_fma_f32 v[40:41], v[20:21], v[94:95], v[40:41] op_sel:[0,1,0] op_sel_hi:[1,1,1]
	v_mul_f32_e32 v50, v100, v51
	v_add_f32_dpp v38, v38, v38 row_ror:8 row_mask:0xf bank_mask:0x3 bound_ctrl:1
	v_add_f32_dpp v39, v39, v39 row_ror:8 row_mask:0xf bank_mask:0x3 bound_ctrl:1
	v_add_f32_dpp v38, v40, v40 row_ror:8 row_mask:0xf bank_mask:0xc bound_ctrl:1
	v_add_f32_dpp v39, v41, v41 row_ror:8 row_mask:0xf bank_mask:0xc bound_ctrl:1
	ds_read_b128 v[56:59], v2 offset:256
	v_add_f32_dpp v38, v38, v38 row_half_mirror row_mask:0xf bank_mask:0x5 bound_ctrl:1
	v_add_f32_dpp v38, v39, v39 row_half_mirror row_mask:0xf bank_mask:0xa bound_ctrl:1
	ds_read_b128 v[60:63], v2 offset:512
	ds_read_b128 v[64:67], v2 offset:768
	v_add_f32_dpp v38, v38, v38 quad_perm:[1,0,3,2] row_mask:0xf bank_mask:0xf bound_ctrl:1
	ds_read_b128 v[68:71], v2 offset:1024
	ds_read_b64 v[72:73], v3 offset:12544
	v_add_f32_dpp v38, v38, v38 quad_perm:[2,3,0,1] row_mask:0xf bank_mask:0xf bound_ctrl:1
	ds_read_b128 v[76:79], v1 offset:14592
	v_cmp_gt_f32_e32 vcc, 0x2b8cbccc, v50
	v_fmac_f32_dpp v96, -v38, v50 row_newbcast:0 row_mask:0xf bank_mask:0xf bound_ctrl:1
	v_fmac_f32_dpp v97, -v38, v50 row_newbcast:4 row_mask:0xf bank_mask:0xf bound_ctrl:1
	v_pk_mul_f32 v[44:45], v[96:97], v[100:101] op_sel:[0,1] op_sel_hi:[1,1]
	v_pk_mul_f32 v[48:49], v[44:45], v[102:103] op_sel_hi:[1,0]
	v_rcp_f32_e32 v52, v50
	s_add_u32 s14, s14, 0x1000
	s_addc_u32 s15, s15, 0
	v_fmac_f32_dpp v48, v38, v50 row_newbcast:8 row_mask:0xf bank_mask:0xf bound_ctrl:1
	v_fmac_f32_dpp v49, v38, v50 row_newbcast:12 row_mask:0xf bank_mask:0xf bound_ctrl:1
	s_cbranch_vccnz .Lgd2_rare2_6
.Lgd2_back2_6:
	v_cvt_pk_bf16_f32 v54, v48, v49
	v_pk_mul_f32 v[46:47], v[44:45], v[52:53] op_sel_hi:[1,0]
	v_pk_fma_f32 v[6:7], v[80:81], v[46:47], v[6:7] op_sel_hi:[0,1,1]
	v_pk_fma_f32 v[8:9], v[82:83], v[46:47], v[8:9] op_sel_hi:[0,1,1]
	v_pk_fma_f32 v[10:11], v[84:85], v[46:47], v[10:11] op_sel_hi:[0,1,1]
	v_pk_fma_f32 v[12:13], v[86:87], v[46:47], v[12:13] op_sel_hi:[0,1,1]
	v_pk_fma_f32 v[14:15], v[88:89], v[46:47], v[14:15] op_sel_hi:[0,1,1]
	v_pk_fma_f32 v[16:17], v[90:91], v[46:47], v[16:17] op_sel_hi:[0,1,1]
	v_pk_fma_f32 v[18:19], v[92:93], v[46:47], v[18:19] op_sel_hi:[0,1,1]
	v_pk_fma_f32 v[20:21], v[94:95], v[46:47], v[20:21] op_sel_hi:[0,1,1]
	global_store_dword v154, v54, s[14:15] offset:-4096
	s_waitcnt lgkmcnt(6)
	v_pk_mul_f32 v[38:39], v[6:7], v[126:127] op_sel_hi:[1,0]
	v_pk_mul_f32 v[40:41], v[6:7], v[126:127] op_sel:[0,1] op_sel_hi:[1,1]
	v_pk_fma_f32 v[38:39], v[8:9], v[128:129], v[38:39] op_sel_hi:[1,0,1]
	v_pk_fma_f32 v[40:41], v[8:9], v[128:129], v[40:41] op_sel:[0,1,0] op_sel_hi:[1,1,1]
	v_pk_fma_f32 v[38:39], v[10:11], v[130:131], v[38:39] op_sel_hi:[1,0,1]
	v_pk_fma_f32 v[40:41], v[10:11], v[130:131], v[40:41] op_sel:[0,1,0] op_sel_hi:[1,1,1]
	v_pk_fma_f32 v[38:39], v[12:13], v[132:133], v[38:39] op_sel_hi:[1,0,1]
	v_pk_fma_f32 v[40:41], v[12:13], v[132:133], v[40:41] op_sel:[0,1,0] op_sel_hi:[1,1,1]
	v_pk_fma_f32 v[38:39], v[14:15], v[134:135], v[38:39] op_sel_hi:[1,0,1]
	v_pk_fma_f32 v[40:41], v[14:15], v[134:135], v[40:41] op_sel:[0,1,0] op_sel_hi:[1,1,1]
	v_pk_fma_f32 v[38:39], v[16:17], v[136:137], v[38:39] op_sel_hi:[1,0,1]
	v_pk_fma_f32 v[40:41], v[16:17], v[136:137], v[40:41] op_sel:[0,1,0] op_sel_hi:[1,1,1]
	v_pk_fma_f32 v[38:39], v[18:19], v[138:139], v[38:39] op_sel_hi:[1,0,1]
	v_pk_fma_f32 v[40:41], v[18:19], v[138:139], v[40:41] op_sel:[0,1,0] op_sel_hi:[1,1,1]
	v_pk_fma_f32 v[38:39], v[20:21], v[140:141], v[38:39] op_sel_hi:[1,0,1]
	v_pk_fma_f32 v[40:41], v[20:21], v[140:141], v[40:41] op_sel:[0,1,0] op_sel_hi:[1,1,1]
	v_mul_f32_e32 v51, v144, v50
	v_add_f32_dpp v38, v38, v38 row_ror:8 row_mask:0xf bank_mask:0x3 bound_ctrl:1
	v_add_f32_dpp v39, v39, v39 row_ror:8 row_mask:0xf bank_mask:0x3 bound_ctrl:1
	v_add_f32_dpp v38, v40, v40 row_ror:8 row_mask:0xf bank_mask:0xc bound_ctrl:1
	v_add_f32_dpp v39, v41, v41 row_ror:8 row_mask:0xf bank_mask:0xc bound_ctrl:1
	ds_read_b128 v[80:83], v2 offset:1280
	v_add_f32_dpp v38, v38, v38 row_half_mirror row_mask:0xf bank_mask:0x5 bound_ctrl:1
	v_add_f32_dpp v38, v39, v39 row_half_mirror row_mask:0xf bank_mask:0xa bound_ctrl:1
	ds_read_b128 v[84:87], v2 offset:1536
	ds_read_b128 v[88:91], v2 offset:1792
	v_add_f32_dpp v38, v38, v38 quad_perm:[1,0,3,2] row_mask:0xf bank_mask:0xf bound_ctrl:1
	ds_read_b128 v[92:95], v2 offset:2048
	ds_read_b64 v[96:97], v3 offset:12800
	v_add_f32_dpp v38, v38, v38 quad_perm:[2,3,0,1] row_mask:0xf bank_mask:0xf bound_ctrl:1
	ds_read_b128 v[100:103], v1 offset:14608
	v_cmp_gt_f32_e32 vcc, 0x2b8cbccc, v51
	v_fmac_f32_dpp v142, -v38, v51 row_newbcast:0 row_mask:0xf bank_mask:0xf bound_ctrl:1
	v_fmac_f32_dpp v143, -v38, v51 row_newbcast:4 row_mask:0xf bank_mask:0xf bound_ctrl:1
	v_pk_mul_f32 v[44:45], v[142:143], v[144:145] op_sel:[0,1] op_sel_hi:[1,1]
	v_pk_mul_f32 v[48:49], v[44:45], v[146:147] op_sel_hi:[1,0]
	v_rcp_f32_e32 v52, v51
	s_add_u32 s14, s14, 0x1000
	s_addc_u32 s15, s15, 0
	v_fmac_f32_dpp v48, v38, v51 row_newbcast:8 row_mask:0xf bank_mask:0xf bound_ctrl:1
	v_fmac_f32_dpp v49, v38, v51 row_newbcast:12 row_mask:0xf bank_mask:0xf bound_ctrl:1
	s_cbranch_vccnz .Lgd2_rare2_7
.Lgd2_back2_7:
	v_cvt_pk_bf16_f32 v54, v48, v49
	v_pk_mul_f32 v[46:47], v[44:45], v[52:53] op_sel_hi:[1,0]
	v_pk_fma_f32 v[6:7], v[126:127], v[46:47], v[6:7] op_sel_hi:[0,1,1]
	v_pk_fma_f32 v[8:9], v[128:129], v[46:47], v[8:9] op_sel_hi:[0,1,1]
	v_pk_fma_f32 v[10:11], v[130:131], v[46:47], v[10:11] op_sel_hi:[0,1,1]
	v_pk_fma_f32 v[12:13], v[132:133], v[46:47], v[12:13] op_sel_hi:[0,1,1]
	v_pk_fma_f32 v[14:15], v[134:135], v[46:47], v[14:15] op_sel_hi:[0,1,1]
	v_pk_fma_f32 v[16:17], v[136:137], v[46:47], v[16:17] op_sel_hi:[0,1,1]
	v_pk_fma_f32 v[18:19], v[138:139], v[46:47], v[18:19] op_sel_hi:[0,1,1]
	v_pk_fma_f32 v[20:21], v[140:141], v[46:47], v[20:21] op_sel_hi:[0,1,1]
	global_store_dword v154, v54, s[14:15] offset:-4096
	s_waitcnt vmcnt(8)
	v_lshlrev_b32_e32 v116, 16, v108
	v_lshlrev_b32_e32 v117, 16, v109
	v_and_b32_e32 v118, s17, v108
	v_and_b32_e32 v119, s17, v109
	v_lshlrev_b32_e32 v120, 16, v110
	v_and_b32_e32 v121, s17, v110
	v_lshlrev_b32_e32 v122, 16, v111
	v_and_b32_e32 v123, s17, v111
	v_lshlrev_b32_e32 v124, 16, v112
	v_and_b32_e32 v125, s17, v112
	ds_write_b128 v32, v[116:119] offset:16640
	ds_write_b64 v33, v[120:121] offset:16640
	ds_write_b64 v34, v[122:123] offset:16640
	ds_write_b64 v34, v[124:125] offset:16768
	ds_write_b32 v35, v113 offset:16640
	s_add_i32 s16, s16, 8
	s_waitcnt lgkmcnt(0)
	s_barrier
	s_cmpk_lt_u32 s16, 0x800
	s_cbranch_scc1 .Lgd2_loop
